# I + nt hint on the residual epilogues' x loads and stores (streamed-once data)
# baseline (speedup 1.0000x reference)
;     __device__ __forceinline__ void operator()(const pg8::f32x4 (&acc)[2][2][4][2], const pg8::Unit& u, int wr, int wc, int fr, int fq) const {
;         const int b = u.pm >> 4;
;         const int row0 = u.pm * 256 + wr * 64 + fr, col0 = u.pn * 256 + wc * 32 + 4 * fq;
;         pg8::f32x4 gv[2][2];
; #pragma unroll
;         for (int bj = 0; bj < 2; ++bj)
; #pragma unroll
;             for (int n = 0; n < 2; ++n) gv[bj][n] = *(const pg8::f32x4*)(gate + (size_t)b * NMOD + col0 + bj * 128 + n * 16) * coef;
; #pragma unroll
;         for (int ai = 0; ai < 2; ++ai)
; #pragma unroll
;             for (int m = 0; m < 4; ++m) { const size_t off = (size_t)(row0 + ai * 128 + m * 16) * D + col0;
; #pragma unroll
;                 for (int bj = 0; bj < 2; ++bj)
; #pragma unroll
;                     for (int n = 0; n < 2; ++n) { const pg8::f32x4 xv = *(const pg8::f32x4*)(xin + off + bj * 128 + n * 16);
;                         *(pg8::f32x4*)(xout + off + bj * 128 + n * 16) = xv + gv[bj][n] * acc[ai][bj][m][n]; }
;                 if (m & 1) asm volatile("" ::: "memory"); }
;     }
.LBB0_361:
	v_and_b32_e32 v136, 0x40, v158
	v_and_b32_e32 v137, 12, v160
	v_or_b32_e32 v136, v136, v137
	v_and_b32_e32 v137, 0x60, v160
	v_and_or_b32 v137, v158, 15, v137
	v_lshlrev_b32_e32 v137, 2, v137
	v_lshl_add_u32 v136, v136, 13, v137
	s_ashr_i32 vcc_hi, s55, 4
	s_mul_i32 vcc_hi, vcc_hi, 0x12000
	s_lshl_b32 vcc_lo, s26, 10
	s_add_u32 vcc_hi, vcc_hi, vcc_lo
	s_add_u32 s16, s46, vcc_hi
	s_addc_u32 s17, s47, 0
	global_load_dword v138, v137, s[16:17]
	global_load_dword v139, v137, s[16:17] offset:64
	global_load_dword v140, v137, s[16:17] offset:512
	global_load_dword v141, v137, s[16:17] offset:576
	s_lshl_b32 vcc_hi, s55, 21
	s_add_u32 vcc_lo, vcc_lo, vcc_hi
	s_add_u32 s100, s0, vcc_lo
	s_addc_u32 s101, s1, 0
	s_add_u32 s16, s8, vcc_lo
	s_addc_u32 s17, s9, 0
	global_load_dword v142, v136, s[100:101] nt
	global_load_dword v143, v136, s[100:101] offset:64 nt
	global_load_dword v144, v136, s[100:101] offset:512 nt
	global_load_dword v145, v136, s[100:101] offset:576 nt
	s_add_u32 s100, s100, 0x2000
	s_addc_u32 s101, s101, 0
	global_load_dword v146, v136, s[100:101] nt
	global_load_dword v147, v136, s[100:101] offset:64 nt
	global_load_dword v148, v136, s[100:101] offset:512 nt
	global_load_dword v149, v136, s[100:101] offset:576 nt
	s_add_u32 s100, s100, 0x2000
	s_addc_u32 s101, s101, 0
	global_load_dword v150, v136, s[100:101] nt
	global_load_dword v151, v136, s[100:101] offset:64 nt
	global_load_dword v152, v136, s[100:101] offset:512 nt
	global_load_dword v153, v136, s[100:101] offset:576 nt
	s_add_u32 s100, s100, 0x2000
	s_addc_u32 s101, s101, 0
	global_load_dword v154, v136, s[100:101] nt
	global_load_dword v155, v136, s[100:101] offset:64 nt
	global_load_dword v162, v136, s[100:101] offset:512 nt
	global_load_dword v163, v136, s[100:101] offset:576 nt
	s_add_u32 s100, s100, 0x1a000
	s_addc_u32 s101, s101, 0
	global_load_dword v164, v136, s[100:101] nt
	global_load_dword v165, v136, s[100:101] offset:64 nt
	global_load_dword v166, v136, s[100:101] offset:512 nt
	global_load_dword v167, v136, s[100:101] offset:576 nt
	s_add_u32 s100, s100, 0x2000
	s_addc_u32 s101, s101, 0
	global_load_dword v168, v136, s[100:101] nt
	global_load_dword v169, v136, s[100:101] offset:64 nt
	global_load_dword v176, v136, s[100:101] offset:512 nt
	global_load_dword v177, v136, s[100:101] offset:576 nt
	s_add_u32 s100, s100, 0x2000
	s_addc_u32 s101, s101, 0
	global_load_dword v178, v136, s[100:101] nt
	global_load_dword v179, v136, s[100:101] offset:64 nt
	global_load_dword v180, v136, s[100:101] offset:512 nt
	global_load_dword v181, v136, s[100:101] offset:576 nt
	s_add_u32 s100, s100, 0x2000
	s_addc_u32 s101, s101, 0
	global_load_dword v182, v136, s[100:101] nt
	global_load_dword v183, v136, s[100:101] offset:64 nt
	global_load_dword v184, v136, s[100:101] offset:512 nt
	global_load_dword v185, v136, s[100:101] offset:576 nt
	s_add_u32 s100, s100, 0x1a000
	s_addc_u32 s101, s101, 0
	s_waitcnt vmcnt(16)
	v_mul_f32_e32 v138, 0.5, v138
	v_mul_f32_e32 v139, 0.5, v139
	v_mul_f32_e32 v140, 0.5, v140
	v_mul_f32_e32 v141, 0.5, v141
	v_fma_f32 v126, v126, v138, v142
	v_fma_f32 v122, v122, v139, v143
	v_fma_f32 v118, v118, v140, v144
	v_fma_f32 v114, v114, v141, v145
	v_fma_f32 v127, v127, v138, v146
	v_fma_f32 v123, v123, v139, v147
	v_fma_f32 v119, v119, v140, v148
	v_fma_f32 v115, v115, v141, v149
	v_fma_f32 v128, v128, v138, v150
	v_fma_f32 v124, v124, v139, v151
	v_fma_f32 v120, v120, v140, v152
	v_fma_f32 v116, v116, v141, v153
	v_fma_f32 v129, v129, v138, v154
	v_fma_f32 v125, v125, v139, v155
	v_fma_f32 v121, v121, v140, v162
	v_fma_f32 v117, v117, v141, v163
	global_store_dword v136, v126, s[16:17] nt
	global_store_dword v136, v122, s[16:17] offset:64 nt
	global_store_dword v136, v118, s[16:17] offset:512 nt
	global_store_dword v136, v114, s[16:17] offset:576 nt
	s_add_u32 s16, s16, 0x2000
	s_addc_u32 s17, s17, 0
	global_store_dword v136, v127, s[16:17] nt
	global_store_dword v136, v123, s[16:17] offset:64 nt
	global_store_dword v136, v119, s[16:17] offset:512 nt
	global_store_dword v136, v115, s[16:17] offset:576 nt
	s_add_u32 s16, s16, 0x2000
	s_addc_u32 s17, s17, 0
	global_store_dword v136, v128, s[16:17] nt
	global_store_dword v136, v124, s[16:17] offset:64 nt
	global_store_dword v136, v120, s[16:17] offset:512 nt
	global_store_dword v136, v116, s[16:17] offset:576 nt
	s_add_u32 s16, s16, 0x2000
	s_addc_u32 s17, s17, 0
	global_store_dword v136, v129, s[16:17] nt
	global_store_dword v136, v125, s[16:17] offset:64 nt
	global_store_dword v136, v121, s[16:17] offset:512 nt
	global_store_dword v136, v117, s[16:17] offset:576 nt
	s_add_u32 s16, s16, 0x1a000
	s_addc_u32 s17, s17, 0
	global_load_dword v142, v136, s[100:101] nt
	global_load_dword v143, v136, s[100:101] offset:64 nt
	global_load_dword v144, v136, s[100:101] offset:512 nt
	global_load_dword v145, v136, s[100:101] offset:576 nt
	s_add_u32 s100, s100, 0x2000
	s_addc_u32 s101, s101, 0
	global_load_dword v146, v136, s[100:101] nt
	global_load_dword v147, v136, s[100:101] offset:64 nt
	global_load_dword v148, v136, s[100:101] offset:512 nt
	global_load_dword v149, v136, s[100:101] offset:576 nt
	s_add_u32 s100, s100, 0x2000
	s_addc_u32 s101, s101, 0
	global_load_dword v150, v136, s[100:101] nt
	global_load_dword v151, v136, s[100:101] offset:64 nt
	global_load_dword v152, v136, s[100:101] offset:512 nt
	global_load_dword v153, v136, s[100:101] offset:576 nt
	s_add_u32 s100, s100, 0x2000
	s_addc_u32 s101, s101, 0
	global_load_dword v154, v136, s[100:101] nt
	global_load_dword v155, v136, s[100:101] offset:64 nt
	global_load_dword v162, v136, s[100:101] offset:512 nt
	global_load_dword v163, v136, s[100:101] offset:576 nt
	s_add_u32 s100, s100, 0x1a000
	s_addc_u32 s101, s101, 0
	s_waitcnt vmcnt(32)
;     __device__ __forceinline__ void operator()(const pg8::f32x4 (&acc)[2][2][4][2], const pg8::Unit& u, int wr, int wc, int fr, int fq) const {
;     ...
;             for (int m = 0; m < 4; ++m) { const size_t off = (size_t)(row0 + ai * 128 + m * 16) * D + col0;
; #pragma unroll
;                 for (int bj = 0; bj < 2; ++bj)
; #pragma unroll
;                     for (int n = 0; n < 2; ++n) { const pg8::f32x4 xv = *(const pg8::f32x4*)(xin + off + bj * 128 + n * 16);
;                         *(pg8::f32x4*)(xout + off + bj * 128 + n * 16) = xv + gv[bj][n] * acc[ai][bj][m][n]; }
;                 if (m & 1) asm volatile("" ::: "memory"); }
;     }
	v_fma_f32 v110, v110, v138, v164
	v_fma_f32 v106, v106, v139, v165
	v_fma_f32 v102, v102, v140, v166
	v_fma_f32 v98, v98, v141, v167
	v_fma_f32 v111, v111, v138, v168
	v_fma_f32 v107, v107, v139, v169
	v_fma_f32 v103, v103, v140, v176
	v_fma_f32 v99, v99, v141, v177
	v_fma_f32 v112, v112, v138, v178
	v_fma_f32 v108, v108, v139, v179
	v_fma_f32 v104, v104, v140, v180
	v_fma_f32 v100, v100, v141, v181
	v_fma_f32 v113, v113, v138, v182
	v_fma_f32 v109, v109, v139, v183
	v_fma_f32 v105, v105, v140, v184
	v_fma_f32 v101, v101, v141, v185
	global_store_dword v136, v110, s[16:17] nt
	global_store_dword v136, v106, s[16:17] offset:64 nt
	global_store_dword v136, v102, s[16:17] offset:512 nt
	global_store_dword v136, v98, s[16:17] offset:576 nt
	s_add_u32 s16, s16, 0x2000
	s_addc_u32 s17, s17, 0
	global_store_dword v136, v111, s[16:17] nt
	global_store_dword v136, v107, s[16:17] offset:64 nt
	global_store_dword v136, v103, s[16:17] offset:512 nt
	global_store_dword v136, v99, s[16:17] offset:576 nt
	s_add_u32 s16, s16, 0x2000
	s_addc_u32 s17, s17, 0
	global_store_dword v136, v112, s[16:17] nt
	global_store_dword v136, v108, s[16:17] offset:64 nt
	global_store_dword v136, v104, s[16:17] offset:512 nt
	global_store_dword v136, v100, s[16:17] offset:576 nt
	s_add_u32 s16, s16, 0x2000
	s_addc_u32 s17, s17, 0
	global_store_dword v136, v113, s[16:17] nt
	global_store_dword v136, v109, s[16:17] offset:64 nt
	global_store_dword v136, v105, s[16:17] offset:512 nt
	global_store_dword v136, v101, s[16:17] offset:576 nt
	s_add_u32 s16, s16, 0x1a000
	s_addc_u32 s17, s17, 0
	global_load_dword v164, v136, s[100:101] nt
	global_load_dword v165, v136, s[100:101] offset:64 nt
	global_load_dword v166, v136, s[100:101] offset:512 nt
	global_load_dword v167, v136, s[100:101] offset:576 nt
	s_add_u32 s100, s100, 0x2000
	s_addc_u32 s101, s101, 0
	global_load_dword v168, v136, s[100:101] nt
	global_load_dword v169, v136, s[100:101] offset:64 nt
	global_load_dword v176, v136, s[100:101] offset:512 nt
	global_load_dword v177, v136, s[100:101] offset:576 nt
	s_add_u32 s100, s100, 0x2000
	s_addc_u32 s101, s101, 0
	global_load_dword v178, v136, s[100:101] nt
	global_load_dword v179, v136, s[100:101] offset:64 nt
	global_load_dword v180, v136, s[100:101] offset:512 nt
	global_load_dword v181, v136, s[100:101] offset:576 nt
	s_add_u32 s100, s100, 0x2000
	s_addc_u32 s101, s101, 0
	global_load_dword v182, v136, s[100:101] nt
	global_load_dword v183, v136, s[100:101] offset:64 nt
	global_load_dword v184, v136, s[100:101] offset:512 nt
	global_load_dword v185, v136, s[100:101] offset:576 nt
	s_add_u32 s100, s100, 0x9a000
	s_addc_u32 s101, s101, 0
	s_waitcnt vmcnt(32)
	v_fma_f32 v94, v94, v138, v142
	v_fma_f32 v90, v90, v139, v143
	v_fma_f32 v86, v86, v140, v144
	v_fma_f32 v82, v82, v141, v145
	v_fma_f32 v95, v95, v138, v146
	v_fma_f32 v91, v91, v139, v147
	v_fma_f32 v87, v87, v140, v148
	v_fma_f32 v83, v83, v141, v149
	v_fma_f32 v96, v96, v138, v150
	v_fma_f32 v92, v92, v139, v151
	v_fma_f32 v88, v88, v140, v152
	v_fma_f32 v84, v84, v141, v153
	v_fma_f32 v97, v97, v138, v154
	v_fma_f32 v93, v93, v139, v155
	v_fma_f32 v89, v89, v140, v162
	v_fma_f32 v85, v85, v141, v163
	global_store_dword v136, v94, s[16:17] nt
	global_store_dword v136, v90, s[16:17] offset:64 nt
	global_store_dword v136, v86, s[16:17] offset:512 nt
	global_store_dword v136, v82, s[16:17] offset:576 nt
	s_add_u32 s16, s16, 0x2000
	s_addc_u32 s17, s17, 0
	global_store_dword v136, v95, s[16:17] nt
	global_store_dword v136, v91, s[16:17] offset:64 nt
	global_store_dword v136, v87, s[16:17] offset:512 nt
	global_store_dword v136, v83, s[16:17] offset:576 nt
	s_add_u32 s16, s16, 0x2000
	s_addc_u32 s17, s17, 0
	global_store_dword v136, v96, s[16:17] nt
	global_store_dword v136, v92, s[16:17] offset:64 nt
	global_store_dword v136, v88, s[16:17] offset:512 nt
	global_store_dword v136, v84, s[16:17] offset:576 nt
	s_add_u32 s16, s16, 0x2000
	s_addc_u32 s17, s17, 0
	global_store_dword v136, v97, s[16:17] nt
	global_store_dword v136, v93, s[16:17] offset:64 nt
	global_store_dword v136, v89, s[16:17] offset:512 nt
	global_store_dword v136, v85, s[16:17] offset:576 nt
	s_add_u32 s16, s16, 0x1a000
	s_addc_u32 s17, s17, 0
	global_load_dword v142, v136, s[100:101] nt
	global_load_dword v143, v136, s[100:101] offset:64 nt
	global_load_dword v144, v136, s[100:101] offset:512 nt
	global_load_dword v145, v136, s[100:101] offset:576 nt
	s_add_u32 s100, s100, 0x2000
	s_addc_u32 s101, s101, 0
	global_load_dword v146, v136, s[100:101] nt
	global_load_dword v147, v136, s[100:101] offset:64 nt
	global_load_dword v148, v136, s[100:101] offset:512 nt
	global_load_dword v149, v136, s[100:101] offset:576 nt
	s_add_u32 s100, s100, 0x2000
	s_addc_u32 s101, s101, 0
	global_load_dword v150, v136, s[100:101] nt
	global_load_dword v151, v136, s[100:101] offset:64 nt
	global_load_dword v152, v136, s[100:101] offset:512 nt
	global_load_dword v153, v136, s[100:101] offset:576 nt
	s_add_u32 s100, s100, 0x2000
	s_addc_u32 s101, s101, 0
	global_load_dword v154, v136, s[100:101] nt
	global_load_dword v155, v136, s[100:101] offset:64 nt
	global_load_dword v162, v136, s[100:101] offset:512 nt
	global_load_dword v163, v136, s[100:101] offset:576 nt
	s_add_u32 s100, s100, 0x1a000
	s_addc_u32 s101, s101, 0
	s_waitcnt vmcnt(32)
;     __device__ __forceinline__ void operator()(const pg8::f32x4 (&acc)[2][2][4][2], const pg8::Unit& u, int wr, int wc, int fr, int fq) const {
;     ...
;             for (int m = 0; m < 4; ++m) { const size_t off = (size_t)(row0 + ai * 128 + m * 16) * D + col0;
; #pragma unroll
;                 for (int bj = 0; bj < 2; ++bj)
; #pragma unroll
;                     for (int n = 0; n < 2; ++n) { const pg8::f32x4 xv = *(const pg8::f32x4*)(xin + off + bj * 128 + n * 16);
;                         *(pg8::f32x4*)(xout + off + bj * 128 + n * 16) = xv + gv[bj][n] * acc[ai][bj][m][n]; }
;                 if (m & 1) asm volatile("" ::: "memory"); }
;     }
	v_fma_f32 v78, v78, v138, v164
	v_fma_f32 v74, v74, v139, v165
	v_fma_f32 v70, v70, v140, v166
	v_fma_f32 v66, v66, v141, v167
	v_fma_f32 v79, v79, v138, v168
	v_fma_f32 v75, v75, v139, v169
	v_fma_f32 v71, v71, v140, v176
	v_fma_f32 v67, v67, v141, v177
	v_fma_f32 v80, v80, v138, v178
	v_fma_f32 v76, v76, v139, v179
	v_fma_f32 v72, v72, v140, v180
	v_fma_f32 v68, v68, v141, v181
	v_fma_f32 v81, v81, v138, v182
	v_fma_f32 v77, v77, v139, v183
	v_fma_f32 v73, v73, v140, v184
	v_fma_f32 v69, v69, v141, v185
	global_store_dword v136, v78, s[16:17] nt
	global_store_dword v136, v74, s[16:17] offset:64 nt
	global_store_dword v136, v70, s[16:17] offset:512 nt
	global_store_dword v136, v66, s[16:17] offset:576 nt
	s_add_u32 s16, s16, 0x2000
	s_addc_u32 s17, s17, 0
	global_store_dword v136, v79, s[16:17] nt
	global_store_dword v136, v75, s[16:17] offset:64 nt
	global_store_dword v136, v71, s[16:17] offset:512 nt
	global_store_dword v136, v67, s[16:17] offset:576 nt
	s_add_u32 s16, s16, 0x2000
	s_addc_u32 s17, s17, 0
	global_store_dword v136, v80, s[16:17] nt
	global_store_dword v136, v76, s[16:17] offset:64 nt
	global_store_dword v136, v72, s[16:17] offset:512 nt
	global_store_dword v136, v68, s[16:17] offset:576 nt
	s_add_u32 s16, s16, 0x2000
	s_addc_u32 s17, s17, 0
	global_store_dword v136, v81, s[16:17] nt
	global_store_dword v136, v77, s[16:17] offset:64 nt
	global_store_dword v136, v73, s[16:17] offset:512 nt
	global_store_dword v136, v69, s[16:17] offset:576 nt
	s_add_u32 s16, s16, 0x9a000
	s_addc_u32 s17, s17, 0
	global_load_dword v164, v136, s[100:101] nt
	global_load_dword v165, v136, s[100:101] offset:64 nt
	global_load_dword v166, v136, s[100:101] offset:512 nt
	global_load_dword v167, v136, s[100:101] offset:576 nt
	s_add_u32 s100, s100, 0x2000
	s_addc_u32 s101, s101, 0
	global_load_dword v168, v136, s[100:101] nt
	global_load_dword v169, v136, s[100:101] offset:64 nt
	global_load_dword v176, v136, s[100:101] offset:512 nt
	global_load_dword v177, v136, s[100:101] offset:576 nt
	s_add_u32 s100, s100, 0x2000
	s_addc_u32 s101, s101, 0
	global_load_dword v178, v136, s[100:101] nt
	global_load_dword v179, v136, s[100:101] offset:64 nt
	global_load_dword v180, v136, s[100:101] offset:512 nt
	global_load_dword v181, v136, s[100:101] offset:576 nt
	s_add_u32 s100, s100, 0x2000
	s_addc_u32 s101, s101, 0
	global_load_dword v182, v136, s[100:101] nt
	global_load_dword v183, v136, s[100:101] offset:64 nt
	global_load_dword v184, v136, s[100:101] offset:512 nt
	global_load_dword v185, v136, s[100:101] offset:576 nt
	s_add_u32 s100, s100, 0x1a000
	s_addc_u32 s101, s101, 0
	s_waitcnt vmcnt(32)
	v_fma_f32 v62, v62, v138, v142
	v_fma_f32 v58, v58, v139, v143
	v_fma_f32 v54, v54, v140, v144
	v_fma_f32 v50, v50, v141, v145
	v_fma_f32 v63, v63, v138, v146
	v_fma_f32 v59, v59, v139, v147
	v_fma_f32 v55, v55, v140, v148
	v_fma_f32 v51, v51, v141, v149
	v_fma_f32 v64, v64, v138, v150
	v_fma_f32 v60, v60, v139, v151
	v_fma_f32 v56, v56, v140, v152
	v_fma_f32 v52, v52, v141, v153
	v_fma_f32 v65, v65, v138, v154
	v_fma_f32 v61, v61, v139, v155
	v_fma_f32 v57, v57, v140, v162
	v_fma_f32 v53, v53, v141, v163
	global_store_dword v136, v62, s[16:17] nt
	global_store_dword v136, v58, s[16:17] offset:64 nt
	global_store_dword v136, v54, s[16:17] offset:512 nt
	global_store_dword v136, v50, s[16:17] offset:576 nt
	s_add_u32 s16, s16, 0x2000
	s_addc_u32 s17, s17, 0
	global_store_dword v136, v63, s[16:17] nt
	global_store_dword v136, v59, s[16:17] offset:64 nt
	global_store_dword v136, v55, s[16:17] offset:512 nt
	global_store_dword v136, v51, s[16:17] offset:576 nt
	s_add_u32 s16, s16, 0x2000
	s_addc_u32 s17, s17, 0
	global_store_dword v136, v64, s[16:17] nt
	global_store_dword v136, v60, s[16:17] offset:64 nt
	global_store_dword v136, v56, s[16:17] offset:512 nt
	global_store_dword v136, v52, s[16:17] offset:576 nt
	s_add_u32 s16, s16, 0x2000
	s_addc_u32 s17, s17, 0
	global_store_dword v136, v65, s[16:17] nt
	global_store_dword v136, v61, s[16:17] offset:64 nt
	global_store_dword v136, v57, s[16:17] offset:512 nt
	global_store_dword v136, v53, s[16:17] offset:576 nt
	s_add_u32 s16, s16, 0x1a000
	s_addc_u32 s17, s17, 0
	global_load_dword v142, v136, s[100:101] nt
	global_load_dword v143, v136, s[100:101] offset:64 nt
	global_load_dword v144, v136, s[100:101] offset:512 nt
	global_load_dword v145, v136, s[100:101] offset:576 nt
	s_add_u32 s100, s100, 0x2000
	s_addc_u32 s101, s101, 0
	global_load_dword v146, v136, s[100:101] nt
	global_load_dword v147, v136, s[100:101] offset:64 nt
	global_load_dword v148, v136, s[100:101] offset:512 nt
	global_load_dword v149, v136, s[100:101] offset:576 nt
	s_add_u32 s100, s100, 0x2000
	s_addc_u32 s101, s101, 0
	global_load_dword v150, v136, s[100:101] nt
	global_load_dword v151, v136, s[100:101] offset:64 nt
	global_load_dword v152, v136, s[100:101] offset:512 nt
	global_load_dword v153, v136, s[100:101] offset:576 nt
	s_add_u32 s100, s100, 0x2000
	s_addc_u32 s101, s101, 0
	global_load_dword v154, v136, s[100:101] nt
	global_load_dword v155, v136, s[100:101] offset:64 nt
	global_load_dword v162, v136, s[100:101] offset:512 nt
	global_load_dword v163, v136, s[100:101] offset:576 nt
	s_add_u32 s100, s100, 0x1a000
	s_addc_u32 s101, s101, 0
	s_waitcnt vmcnt(32)
; #define PG8_BAR __builtin_amdgcn_s_barrier()
; template <class Epi, class Sched, bool ALIGN_EPI = false, bool SP2 = false>
; __device__ __forceinline__ void gemm_phase(PG8_LAS unsigned char* lds, const Gemm g, const Sched& S, const Epi& E, int wave_s) {
;     ...
;         if constexpr (ALIGN_EPI) { if (wr == 0) PG8_BAR; }
;         E(acc, cur, wr, wc, fr, fq); S.done(cur);
;         if (!has_next) break;
; #pragma unroll
;         for (int a = 0; a < 2; ++a)
; #pragma unroll
;             for (int b = 0; b < 2; ++b)
; #pragma unroll
;                 for (int m = 0; m < 4; ++m)
; #pragma unroll
;                     for (int n = 0; n < 2; ++n) acc[a][b][m][n] = (f32x4){0.f, 0.f, 0.f, 0.f};
;         cur = nxt; cA = nA; cB = nB; ++ui;
;         if constexpr (ALIGN_EPI) { if (wr == 1) PG8_BAR; }
;     __device__ __forceinline__ void operator()(const pg8::f32x4 (&acc)[2][2][4][2], const pg8::Unit& u, int wr, int wc, int fr, int fq) const {
;     ...
;             for (int m = 0; m < 4; ++m) { const size_t off = (size_t)(row0 + ai * 128 + m * 16) * D + col0;
; #pragma unroll
;                 for (int bj = 0; bj < 2; ++bj)
; #pragma unroll
;                     for (int n = 0; n < 2; ++n) { const pg8::f32x4 xv = *(const pg8::f32x4*)(xin + off + bj * 128 + n * 16);
;                         *(pg8::f32x4*)(xout + off + bj * 128 + n * 16) = xv + gv[bj][n] * acc[ai][bj][m][n]; }
;                 if (m & 1) asm volatile("" ::: "memory"); }
;     }
	v_fma_f32 v46, v46, v138, v164
	v_fma_f32 v42, v42, v139, v165
	v_fma_f32 v38, v38, v140, v166
	v_fma_f32 v34, v34, v141, v167
	v_fma_f32 v47, v47, v138, v168
	v_fma_f32 v43, v43, v139, v169
	v_fma_f32 v39, v39, v140, v176
	v_fma_f32 v35, v35, v141, v177
	v_fma_f32 v48, v48, v138, v178
	v_fma_f32 v44, v44, v139, v179
	v_fma_f32 v40, v40, v140, v180
	v_fma_f32 v36, v36, v141, v181
	v_fma_f32 v49, v49, v138, v182
	v_fma_f32 v45, v45, v139, v183
	v_fma_f32 v41, v41, v140, v184
	v_fma_f32 v37, v37, v141, v185
	global_store_dword v136, v46, s[16:17] nt
	global_store_dword v136, v42, s[16:17] offset:64 nt
	global_store_dword v136, v38, s[16:17] offset:512 nt
	global_store_dword v136, v34, s[16:17] offset:576 nt
	s_add_u32 s16, s16, 0x2000
	s_addc_u32 s17, s17, 0
	global_store_dword v136, v47, s[16:17] nt
	global_store_dword v136, v43, s[16:17] offset:64 nt
	global_store_dword v136, v39, s[16:17] offset:512 nt
	global_store_dword v136, v35, s[16:17] offset:576 nt
	s_add_u32 s16, s16, 0x2000
	s_addc_u32 s17, s17, 0
	global_store_dword v136, v48, s[16:17] nt
	global_store_dword v136, v44, s[16:17] offset:64 nt
	global_store_dword v136, v40, s[16:17] offset:512 nt
	global_store_dword v136, v36, s[16:17] offset:576 nt
	s_add_u32 s16, s16, 0x2000
	s_addc_u32 s17, s17, 0
	global_store_dword v136, v49, s[16:17] nt
	global_store_dword v136, v45, s[16:17] offset:64 nt
	global_store_dword v136, v41, s[16:17] offset:512 nt
	global_store_dword v136, v37, s[16:17] offset:576 nt
	s_add_u32 s16, s16, 0x1a000
	s_addc_u32 s17, s17, 0
	global_load_dword v164, v136, s[100:101] nt
	global_load_dword v165, v136, s[100:101] offset:64 nt
	global_load_dword v166, v136, s[100:101] offset:512 nt
	global_load_dword v167, v136, s[100:101] offset:576 nt
	s_add_u32 s100, s100, 0x2000
	s_addc_u32 s101, s101, 0
	global_load_dword v168, v136, s[100:101] nt
	global_load_dword v169, v136, s[100:101] offset:64 nt
	global_load_dword v176, v136, s[100:101] offset:512 nt
	global_load_dword v177, v136, s[100:101] offset:576 nt
	s_add_u32 s100, s100, 0x2000
	s_addc_u32 s101, s101, 0
	global_load_dword v178, v136, s[100:101] nt
	global_load_dword v179, v136, s[100:101] offset:64 nt
	global_load_dword v180, v136, s[100:101] offset:512 nt
	global_load_dword v181, v136, s[100:101] offset:576 nt
	s_add_u32 s100, s100, 0x2000
	s_addc_u32 s101, s101, 0
	global_load_dword v182, v136, s[100:101] nt
	global_load_dword v183, v136, s[100:101] offset:64 nt
	global_load_dword v184, v136, s[100:101] offset:512 nt
	global_load_dword v185, v136, s[100:101] offset:576 nt
	s_waitcnt vmcnt(32)
	v_fma_f32 v30, v30, v138, v142
	v_fma_f32 v26, v26, v139, v143
	v_fma_f32 v22, v22, v140, v144
	v_fma_f32 v18, v18, v141, v145
	v_fma_f32 v31, v31, v138, v146
	v_fma_f32 v27, v27, v139, v147
	v_fma_f32 v23, v23, v140, v148
	v_fma_f32 v19, v19, v141, v149
	v_fma_f32 v32, v32, v138, v150
	v_fma_f32 v28, v28, v139, v151
	v_fma_f32 v24, v24, v140, v152
	v_fma_f32 v20, v20, v141, v153
	v_fma_f32 v33, v33, v138, v154
	v_fma_f32 v29, v29, v139, v155
	v_fma_f32 v25, v25, v140, v162
	v_fma_f32 v21, v21, v141, v163
	global_store_dword v136, v30, s[16:17] nt
	global_store_dword v136, v26, s[16:17] offset:64 nt
	global_store_dword v136, v22, s[16:17] offset:512 nt
	global_store_dword v136, v18, s[16:17] offset:576 nt
	s_add_u32 s16, s16, 0x2000
	s_addc_u32 s17, s17, 0
	global_store_dword v136, v31, s[16:17] nt
	global_store_dword v136, v27, s[16:17] offset:64 nt
	global_store_dword v136, v23, s[16:17] offset:512 nt
	global_store_dword v136, v19, s[16:17] offset:576 nt
	s_add_u32 s16, s16, 0x2000
	s_addc_u32 s17, s17, 0
	global_store_dword v136, v32, s[16:17] nt
	global_store_dword v136, v28, s[16:17] offset:64 nt
	global_store_dword v136, v24, s[16:17] offset:512 nt
	global_store_dword v136, v20, s[16:17] offset:576 nt
	s_add_u32 s16, s16, 0x2000
	s_addc_u32 s17, s17, 0
	global_store_dword v136, v33, s[16:17] nt
	global_store_dword v136, v29, s[16:17] offset:64 nt
	global_store_dword v136, v25, s[16:17] offset:512 nt
	global_store_dword v136, v21, s[16:17] offset:576 nt
	s_add_u32 s16, s16, 0x1a000
	s_addc_u32 s17, s17, 0
	s_waitcnt vmcnt(16)
	v_fma_f32 v14, v14, v138, v164
	v_fma_f32 v10, v10, v139, v165
	v_fma_f32 v6, v6, v140, v166
	v_fma_f32 v2, v2, v141, v167
	v_fma_f32 v15, v15, v138, v168
	v_fma_f32 v11, v11, v139, v169
	v_fma_f32 v7, v7, v140, v176
	v_fma_f32 v3, v3, v141, v177
	v_fma_f32 v16, v16, v138, v178
	v_fma_f32 v12, v12, v139, v179
	v_fma_f32 v8, v8, v140, v180
	v_fma_f32 v4, v4, v141, v181
	v_fma_f32 v17, v17, v138, v182
	v_fma_f32 v13, v13, v139, v183
	v_fma_f32 v9, v9, v140, v184
	v_fma_f32 v5, v5, v141, v185
	global_store_dword v136, v14, s[16:17] nt
	global_store_dword v136, v10, s[16:17] offset:64 nt
	global_store_dword v136, v6, s[16:17] offset:512 nt
	global_store_dword v136, v2, s[16:17] offset:576 nt
	s_add_u32 s16, s16, 0x2000
	s_addc_u32 s17, s17, 0
	global_store_dword v136, v15, s[16:17] nt
	global_store_dword v136, v11, s[16:17] offset:64 nt
	global_store_dword v136, v7, s[16:17] offset:512 nt
	global_store_dword v136, v3, s[16:17] offset:576 nt
	s_add_u32 s16, s16, 0x2000
	s_addc_u32 s17, s17, 0
	global_store_dword v136, v16, s[16:17] nt
	global_store_dword v136, v12, s[16:17] offset:64 nt
	global_store_dword v136, v8, s[16:17] offset:512 nt
	global_store_dword v136, v4, s[16:17] offset:576 nt
	s_add_u32 s16, s16, 0x2000
	s_addc_u32 s17, s17, 0
	global_store_dword v136, v17, s[16:17] nt
	global_store_dword v136, v13, s[16:17] offset:64 nt
	global_store_dword v136, v9, s[16:17] offset:512 nt
	global_store_dword v136, v5, s[16:17] offset:576 nt
	s_mov_b64 s[16:17], -1
	s_and_b64 vcc, exec, s[38:39]
	s_cbranch_vccnz .LBB0_346
	s_andn2_b64 vcc, exec, s[6:7]
	s_cbranch_vccnz .LBB0_345
	s_barrier
	s_branch .LBB0_345

;     __device__ __forceinline__ void operator()(const pg8::f32x4 (&acc)[2][2][4][2], const pg8::Unit& u, int wr, int wc, int fr, int fq) const {
;         const int b = u.pm >> 4;
;         const int row0 = u.pm * 256 + wr * 64 + fr, col0 = u.pn * 256 + wc * 32 + 4 * fq;
;         pg8::f32x4 gv[2][2];
; #pragma unroll
;         for (int bj = 0; bj < 2; ++bj)
; #pragma unroll
;             for (int n = 0; n < 2; ++n) gv[bj][n] = *(const pg8::f32x4*)(gate + (size_t)b * NMOD + col0 + bj * 128 + n * 16) * coef;
; #pragma unroll
;         for (int ai = 0; ai < 2; ++ai)
; #pragma unroll
;             for (int m = 0; m < 4; ++m) { const size_t off = (size_t)(row0 + ai * 128 + m * 16) * D + col0;
; #pragma unroll
;                 for (int bj = 0; bj < 2; ++bj)
; #pragma unroll
;                     for (int n = 0; n < 2; ++n) { const pg8::f32x4 xv = *(const pg8::f32x4*)(xin + off + bj * 128 + n * 16);
;                         *(pg8::f32x4*)(xout + off + bj * 128 + n * 16) = xv + gv[bj][n] * acc[ai][bj][m][n]; }
;                 if (m & 1) asm volatile("" ::: "memory"); }
;     }
.LBB0_1677:
	v_and_b32_e32 v74, 0x40, v158
	v_and_b32_e32 v75, 12, v160
	v_or_b32_e32 v74, v74, v75
	v_and_b32_e32 v75, 0x60, v160
	v_and_or_b32 v75, v158, 15, v75
	v_lshlrev_b32_e32 v75, 2, v75
	v_lshl_add_u32 v74, v74, 13, v75
	s_ashr_i32 vcc_hi, s26, 4
	s_mul_i32 vcc_hi, vcc_hi, 0x12000
	s_lshl_b32 vcc_lo, s27, 10
	s_add_u32 vcc_hi, vcc_hi, vcc_lo
	s_add_u32 s18, s46, vcc_hi
	s_addc_u32 s19, s47, 0
	global_load_dword v76, v75, s[18:19]
	global_load_dword v77, v75, s[18:19] offset:64
	global_load_dword v86, v75, s[18:19] offset:512
	global_load_dword v87, v75, s[18:19] offset:576
	s_lshl_b32 vcc_hi, s26, 21
	s_add_u32 vcc_lo, vcc_lo, vcc_hi
	s_add_u32 s100, s6, vcc_lo
	s_addc_u32 s101, s7, 0
	s_add_u32 s18, s6, vcc_lo
	s_addc_u32 s19, s7, 0
	global_load_dword v88, v74, s[100:101] nt
	global_load_dword v89, v74, s[100:101] offset:64 nt
	global_load_dword v90, v74, s[100:101] offset:512 nt
	global_load_dword v91, v74, s[100:101] offset:576 nt
	s_add_u32 s100, s100, 0x2000
	s_addc_u32 s101, s101, 0
	global_load_dword v92, v74, s[100:101] nt
	global_load_dword v93, v74, s[100:101] offset:64 nt
	global_load_dword v94, v74, s[100:101] offset:512 nt
	global_load_dword v95, v74, s[100:101] offset:576 nt
	s_add_u32 s100, s100, 0x2000
	s_addc_u32 s101, s101, 0
	global_load_dword v96, v74, s[100:101] nt
	global_load_dword v97, v74, s[100:101] offset:64 nt
	global_load_dword v152, v74, s[100:101] offset:512 nt
	global_load_dword v153, v74, s[100:101] offset:576 nt
	s_add_u32 s100, s100, 0x2000
	s_addc_u32 s101, s101, 0
	global_load_dword v154, v74, s[100:101] nt
	global_load_dword v155, v74, s[100:101] offset:64 nt
	global_load_dword v162, v74, s[100:101] offset:512 nt
	global_load_dword v163, v74, s[100:101] offset:576 nt
	s_add_u32 s100, s100, 0x1a000
	s_addc_u32 s101, s101, 0
	global_load_dword v164, v74, s[100:101] nt
	global_load_dword v165, v74, s[100:101] offset:64 nt
	global_load_dword v166, v74, s[100:101] offset:512 nt
	global_load_dword v167, v74, s[100:101] offset:576 nt
	s_add_u32 s100, s100, 0x2000
	s_addc_u32 s101, s101, 0
	global_load_dword v168, v74, s[100:101] nt
	global_load_dword v169, v74, s[100:101] offset:64 nt
	global_load_dword v176, v74, s[100:101] offset:512 nt
	global_load_dword v177, v74, s[100:101] offset:576 nt
	s_add_u32 s100, s100, 0x2000
	s_addc_u32 s101, s101, 0
	global_load_dword v178, v74, s[100:101] nt
	global_load_dword v179, v74, s[100:101] offset:64 nt
	global_load_dword v180, v74, s[100:101] offset:512 nt
	global_load_dword v181, v74, s[100:101] offset:576 nt
	s_add_u32 s100, s100, 0x2000
	s_addc_u32 s101, s101, 0
	global_load_dword v182, v74, s[100:101] nt
	global_load_dword v183, v74, s[100:101] offset:64 nt
	global_load_dword v184, v74, s[100:101] offset:512 nt
	global_load_dword v185, v74, s[100:101] offset:576 nt
	s_add_u32 s100, s100, 0x1a000
	s_addc_u32 s101, s101, 0
	s_waitcnt vmcnt(16)
	v_fma_f32 v142, v142, v76, v88
	v_fma_f32 v138, v138, v77, v89
	v_fma_f32 v134, v134, v86, v90
	v_fma_f32 v130, v130, v87, v91
	v_fma_f32 v143, v143, v76, v92
	v_fma_f32 v139, v139, v77, v93
	v_fma_f32 v135, v135, v86, v94
	v_fma_f32 v131, v131, v87, v95
	v_fma_f32 v144, v144, v76, v96
	v_fma_f32 v140, v140, v77, v97
	v_fma_f32 v136, v136, v86, v152
	v_fma_f32 v132, v132, v87, v153
	v_fma_f32 v145, v145, v76, v154
	v_fma_f32 v141, v141, v77, v155
	v_fma_f32 v137, v137, v86, v162
	v_fma_f32 v133, v133, v87, v163
	global_store_dword v74, v142, s[18:19] nt
	global_store_dword v74, v138, s[18:19] offset:64 nt
	global_store_dword v74, v134, s[18:19] offset:512 nt
	global_store_dword v74, v130, s[18:19] offset:576 nt
	s_add_u32 s18, s18, 0x2000
	s_addc_u32 s19, s19, 0
	global_store_dword v74, v143, s[18:19] nt
	global_store_dword v74, v139, s[18:19] offset:64 nt
	global_store_dword v74, v135, s[18:19] offset:512 nt
	global_store_dword v74, v131, s[18:19] offset:576 nt
	s_add_u32 s18, s18, 0x2000
	s_addc_u32 s19, s19, 0
	global_store_dword v74, v144, s[18:19] nt
	global_store_dword v74, v140, s[18:19] offset:64 nt
	global_store_dword v74, v136, s[18:19] offset:512 nt
	global_store_dword v74, v132, s[18:19] offset:576 nt
	s_add_u32 s18, s18, 0x2000
	s_addc_u32 s19, s19, 0
	global_store_dword v74, v145, s[18:19] nt
	global_store_dword v74, v141, s[18:19] offset:64 nt
	global_store_dword v74, v137, s[18:19] offset:512 nt
	global_store_dword v74, v133, s[18:19] offset:576 nt
	s_add_u32 s18, s18, 0x1a000
	s_addc_u32 s19, s19, 0
	global_load_dword v88, v74, s[100:101] nt
	global_load_dword v89, v74, s[100:101] offset:64 nt
	global_load_dword v90, v74, s[100:101] offset:512 nt
	global_load_dword v91, v74, s[100:101] offset:576 nt
	s_add_u32 s100, s100, 0x2000
	s_addc_u32 s101, s101, 0
	global_load_dword v92, v74, s[100:101] nt
	global_load_dword v93, v74, s[100:101] offset:64 nt
	global_load_dword v94, v74, s[100:101] offset:512 nt
	global_load_dword v95, v74, s[100:101] offset:576 nt
	s_add_u32 s100, s100, 0x2000
	s_addc_u32 s101, s101, 0
	global_load_dword v96, v74, s[100:101] nt
	global_load_dword v97, v74, s[100:101] offset:64 nt
	global_load_dword v152, v74, s[100:101] offset:512 nt
	global_load_dword v153, v74, s[100:101] offset:576 nt
	s_add_u32 s100, s100, 0x2000
	s_addc_u32 s101, s101, 0
	global_load_dword v154, v74, s[100:101] nt
	global_load_dword v155, v74, s[100:101] offset:64 nt
	global_load_dword v162, v74, s[100:101] offset:512 nt
	global_load_dword v163, v74, s[100:101] offset:576 nt
	s_add_u32 s100, s100, 0x1a000
	s_addc_u32 s101, s101, 0
	s_waitcnt vmcnt(32)
;     __device__ __forceinline__ void operator()(const pg8::f32x4 (&acc)[2][2][4][2], const pg8::Unit& u, int wr, int wc, int fr, int fq) const {
;     ...
;             for (int m = 0; m < 4; ++m) { const size_t off = (size_t)(row0 + ai * 128 + m * 16) * D + col0;
; #pragma unroll
;                 for (int bj = 0; bj < 2; ++bj)
; #pragma unroll
;                     for (int n = 0; n < 2; ++n) { const pg8::f32x4 xv = *(const pg8::f32x4*)(xin + off + bj * 128 + n * 16);
;                         *(pg8::f32x4*)(xout + off + bj * 128 + n * 16) = xv + gv[bj][n] * acc[ai][bj][m][n]; }
;                 if (m & 1) asm volatile("" ::: "memory"); }
;     }
	v_fma_f32 v126, v126, v76, v164
	v_fma_f32 v122, v122, v77, v165
	v_fma_f32 v118, v118, v86, v166
	v_fma_f32 v114, v114, v87, v167
	v_fma_f32 v127, v127, v76, v168
	v_fma_f32 v123, v123, v77, v169
	v_fma_f32 v119, v119, v86, v176
	v_fma_f32 v115, v115, v87, v177
	v_fma_f32 v128, v128, v76, v178
	v_fma_f32 v124, v124, v77, v179
	v_fma_f32 v120, v120, v86, v180
	v_fma_f32 v116, v116, v87, v181
	v_fma_f32 v129, v129, v76, v182
	v_fma_f32 v125, v125, v77, v183
	v_fma_f32 v121, v121, v86, v184
	v_fma_f32 v117, v117, v87, v185
	global_store_dword v74, v126, s[18:19] nt
	global_store_dword v74, v122, s[18:19] offset:64 nt
	global_store_dword v74, v118, s[18:19] offset:512 nt
	global_store_dword v74, v114, s[18:19] offset:576 nt
	s_add_u32 s18, s18, 0x2000
	s_addc_u32 s19, s19, 0
	global_store_dword v74, v127, s[18:19] nt
	global_store_dword v74, v123, s[18:19] offset:64 nt
	global_store_dword v74, v119, s[18:19] offset:512 nt
	global_store_dword v74, v115, s[18:19] offset:576 nt
	s_add_u32 s18, s18, 0x2000
	s_addc_u32 s19, s19, 0
	global_store_dword v74, v128, s[18:19] nt
	global_store_dword v74, v124, s[18:19] offset:64 nt
	global_store_dword v74, v120, s[18:19] offset:512 nt
	global_store_dword v74, v116, s[18:19] offset:576 nt
	s_add_u32 s18, s18, 0x2000
	s_addc_u32 s19, s19, 0
	global_store_dword v74, v129, s[18:19] nt
	global_store_dword v74, v125, s[18:19] offset:64 nt
	global_store_dword v74, v121, s[18:19] offset:512 nt
	global_store_dword v74, v117, s[18:19] offset:576 nt
	s_add_u32 s18, s18, 0x1a000
	s_addc_u32 s19, s19, 0
	global_load_dword v164, v74, s[100:101] nt
	global_load_dword v165, v74, s[100:101] offset:64 nt
	global_load_dword v166, v74, s[100:101] offset:512 nt
	global_load_dword v167, v74, s[100:101] offset:576 nt
	s_add_u32 s100, s100, 0x2000
	s_addc_u32 s101, s101, 0
	global_load_dword v168, v74, s[100:101] nt
	global_load_dword v169, v74, s[100:101] offset:64 nt
	global_load_dword v176, v74, s[100:101] offset:512 nt
	global_load_dword v177, v74, s[100:101] offset:576 nt
	s_add_u32 s100, s100, 0x2000
	s_addc_u32 s101, s101, 0
	global_load_dword v178, v74, s[100:101] nt
	global_load_dword v179, v74, s[100:101] offset:64 nt
	global_load_dword v180, v74, s[100:101] offset:512 nt
	global_load_dword v181, v74, s[100:101] offset:576 nt
	s_add_u32 s100, s100, 0x2000
	s_addc_u32 s101, s101, 0
	global_load_dword v182, v74, s[100:101] nt
	global_load_dword v183, v74, s[100:101] offset:64 nt
	global_load_dword v184, v74, s[100:101] offset:512 nt
	global_load_dword v185, v74, s[100:101] offset:576 nt
	s_add_u32 s100, s100, 0x9a000
	s_addc_u32 s101, s101, 0
	s_waitcnt vmcnt(32)
	v_fma_f32 v110, v110, v76, v88
	v_fma_f32 v106, v106, v77, v89
	v_fma_f32 v102, v102, v86, v90
	v_fma_f32 v98, v98, v87, v91
	v_fma_f32 v111, v111, v76, v92
	v_fma_f32 v107, v107, v77, v93
	v_fma_f32 v103, v103, v86, v94
	v_fma_f32 v99, v99, v87, v95
	v_fma_f32 v112, v112, v76, v96
	v_fma_f32 v108, v108, v77, v97
	v_fma_f32 v104, v104, v86, v152
	v_fma_f32 v100, v100, v87, v153
	v_fma_f32 v113, v113, v76, v154
	v_fma_f32 v109, v109, v77, v155
	v_fma_f32 v105, v105, v86, v162
	v_fma_f32 v101, v101, v87, v163
	global_store_dword v74, v110, s[18:19] nt
	global_store_dword v74, v106, s[18:19] offset:64 nt
	global_store_dword v74, v102, s[18:19] offset:512 nt
	global_store_dword v74, v98, s[18:19] offset:576 nt
	s_add_u32 s18, s18, 0x2000
	s_addc_u32 s19, s19, 0
	global_store_dword v74, v111, s[18:19] nt
	global_store_dword v74, v107, s[18:19] offset:64 nt
	global_store_dword v74, v103, s[18:19] offset:512 nt
	global_store_dword v74, v99, s[18:19] offset:576 nt
	s_add_u32 s18, s18, 0x2000
	s_addc_u32 s19, s19, 0
	global_store_dword v74, v112, s[18:19] nt
	global_store_dword v74, v108, s[18:19] offset:64 nt
	global_store_dword v74, v104, s[18:19] offset:512 nt
	global_store_dword v74, v100, s[18:19] offset:576 nt
	s_add_u32 s18, s18, 0x2000
	s_addc_u32 s19, s19, 0
	global_store_dword v74, v113, s[18:19] nt
	global_store_dword v74, v109, s[18:19] offset:64 nt
	global_store_dword v74, v105, s[18:19] offset:512 nt
	global_store_dword v74, v101, s[18:19] offset:576 nt
	s_add_u32 s18, s18, 0x1a000
	s_addc_u32 s19, s19, 0
	global_load_dword v88, v74, s[100:101] nt
	global_load_dword v89, v74, s[100:101] offset:64 nt
	global_load_dword v90, v74, s[100:101] offset:512 nt
	global_load_dword v91, v74, s[100:101] offset:576 nt
	s_add_u32 s100, s100, 0x2000
	s_addc_u32 s101, s101, 0
	global_load_dword v92, v74, s[100:101] nt
	global_load_dword v93, v74, s[100:101] offset:64 nt
	global_load_dword v94, v74, s[100:101] offset:512 nt
	global_load_dword v95, v74, s[100:101] offset:576 nt
	s_add_u32 s100, s100, 0x2000
	s_addc_u32 s101, s101, 0
	global_load_dword v96, v74, s[100:101] nt
	global_load_dword v97, v74, s[100:101] offset:64 nt
	global_load_dword v152, v74, s[100:101] offset:512 nt
	global_load_dword v153, v74, s[100:101] offset:576 nt
	s_add_u32 s100, s100, 0x2000
	s_addc_u32 s101, s101, 0
	global_load_dword v154, v74, s[100:101] nt
	global_load_dword v155, v74, s[100:101] offset:64 nt
	global_load_dword v162, v74, s[100:101] offset:512 nt
	global_load_dword v163, v74, s[100:101] offset:576 nt
	s_add_u32 s100, s100, 0x1a000
	s_addc_u32 s101, s101, 0
	s_waitcnt vmcnt(32)
;     __device__ __forceinline__ void operator()(const pg8::f32x4 (&acc)[2][2][4][2], const pg8::Unit& u, int wr, int wc, int fr, int fq) const {
;     ...
;             for (int m = 0; m < 4; ++m) { const size_t off = (size_t)(row0 + ai * 128 + m * 16) * D + col0;
; #pragma unroll
;                 for (int bj = 0; bj < 2; ++bj)
; #pragma unroll
;                     for (int n = 0; n < 2; ++n) { const pg8::f32x4 xv = *(const pg8::f32x4*)(xin + off + bj * 128 + n * 16);
;                         *(pg8::f32x4*)(xout + off + bj * 128 + n * 16) = xv + gv[bj][n] * acc[ai][bj][m][n]; }
;                 if (m & 1) asm volatile("" ::: "memory"); }
;     }
	v_fma_f32 v82, v82, v76, v164
	v_fma_f32 v78, v78, v77, v165
	v_fma_f32 v70, v70, v86, v166
	v_fma_f32 v66, v66, v87, v167
	v_fma_f32 v83, v83, v76, v168
	v_fma_f32 v79, v79, v77, v169
	v_fma_f32 v71, v71, v86, v176
	v_fma_f32 v67, v67, v87, v177
	v_fma_f32 v84, v84, v76, v178
	v_fma_f32 v80, v80, v77, v179
	v_fma_f32 v72, v72, v86, v180
	v_fma_f32 v68, v68, v87, v181
	v_fma_f32 v85, v85, v76, v182
	v_fma_f32 v81, v81, v77, v183
	v_fma_f32 v73, v73, v86, v184
	v_fma_f32 v69, v69, v87, v185
	global_store_dword v74, v82, s[18:19] nt
	global_store_dword v74, v78, s[18:19] offset:64 nt
	global_store_dword v74, v70, s[18:19] offset:512 nt
	global_store_dword v74, v66, s[18:19] offset:576 nt
	s_add_u32 s18, s18, 0x2000
	s_addc_u32 s19, s19, 0
	global_store_dword v74, v83, s[18:19] nt
	global_store_dword v74, v79, s[18:19] offset:64 nt
	global_store_dword v74, v71, s[18:19] offset:512 nt
	global_store_dword v74, v67, s[18:19] offset:576 nt
	s_add_u32 s18, s18, 0x2000
	s_addc_u32 s19, s19, 0
	global_store_dword v74, v84, s[18:19] nt
	global_store_dword v74, v80, s[18:19] offset:64 nt
	global_store_dword v74, v72, s[18:19] offset:512 nt
	global_store_dword v74, v68, s[18:19] offset:576 nt
	s_add_u32 s18, s18, 0x2000
	s_addc_u32 s19, s19, 0
	global_store_dword v74, v85, s[18:19] nt
	global_store_dword v74, v81, s[18:19] offset:64 nt
	global_store_dword v74, v73, s[18:19] offset:512 nt
	global_store_dword v74, v69, s[18:19] offset:576 nt
	s_add_u32 s18, s18, 0x9a000
	s_addc_u32 s19, s19, 0
	global_load_dword v164, v74, s[100:101] nt
	global_load_dword v165, v74, s[100:101] offset:64 nt
	global_load_dword v166, v74, s[100:101] offset:512 nt
	global_load_dword v167, v74, s[100:101] offset:576 nt
	s_add_u32 s100, s100, 0x2000
	s_addc_u32 s101, s101, 0
	global_load_dword v168, v74, s[100:101] nt
	global_load_dword v169, v74, s[100:101] offset:64 nt
	global_load_dword v176, v74, s[100:101] offset:512 nt
	global_load_dword v177, v74, s[100:101] offset:576 nt
	s_add_u32 s100, s100, 0x2000
	s_addc_u32 s101, s101, 0
	global_load_dword v178, v74, s[100:101] nt
	global_load_dword v179, v74, s[100:101] offset:64 nt
	global_load_dword v180, v74, s[100:101] offset:512 nt
	global_load_dword v181, v74, s[100:101] offset:576 nt
	s_add_u32 s100, s100, 0x2000
	s_addc_u32 s101, s101, 0
	global_load_dword v182, v74, s[100:101] nt
	global_load_dword v183, v74, s[100:101] offset:64 nt
	global_load_dword v184, v74, s[100:101] offset:512 nt
	global_load_dword v185, v74, s[100:101] offset:576 nt
	s_add_u32 s100, s100, 0x1a000
	s_addc_u32 s101, s101, 0
	s_waitcnt vmcnt(32)
	v_fma_f32 v62, v62, v76, v88
	v_fma_f32 v58, v58, v77, v89
	v_fma_f32 v54, v54, v86, v90
	v_fma_f32 v50, v50, v87, v91
	v_fma_f32 v63, v63, v76, v92
	v_fma_f32 v59, v59, v77, v93
	v_fma_f32 v55, v55, v86, v94
	v_fma_f32 v51, v51, v87, v95
	v_fma_f32 v64, v64, v76, v96
	v_fma_f32 v60, v60, v77, v97
	v_fma_f32 v56, v56, v86, v152
	v_fma_f32 v52, v52, v87, v153
	v_fma_f32 v65, v65, v76, v154
	v_fma_f32 v61, v61, v77, v155
	v_fma_f32 v57, v57, v86, v162
	v_fma_f32 v53, v53, v87, v163
	global_store_dword v74, v62, s[18:19] nt
	global_store_dword v74, v58, s[18:19] offset:64 nt
	global_store_dword v74, v54, s[18:19] offset:512 nt
	global_store_dword v74, v50, s[18:19] offset:576 nt
	s_add_u32 s18, s18, 0x2000
	s_addc_u32 s19, s19, 0
	global_store_dword v74, v63, s[18:19] nt
	global_store_dword v74, v59, s[18:19] offset:64 nt
	global_store_dword v74, v55, s[18:19] offset:512 nt
	global_store_dword v74, v51, s[18:19] offset:576 nt
	s_add_u32 s18, s18, 0x2000
	s_addc_u32 s19, s19, 0
	global_store_dword v74, v64, s[18:19] nt
	global_store_dword v74, v60, s[18:19] offset:64 nt
	global_store_dword v74, v56, s[18:19] offset:512 nt
	global_store_dword v74, v52, s[18:19] offset:576 nt
	s_add_u32 s18, s18, 0x2000
	s_addc_u32 s19, s19, 0
	global_store_dword v74, v65, s[18:19] nt
	global_store_dword v74, v61, s[18:19] offset:64 nt
	global_store_dword v74, v57, s[18:19] offset:512 nt
	global_store_dword v74, v53, s[18:19] offset:576 nt
	s_add_u32 s18, s18, 0x1a000
	s_addc_u32 s19, s19, 0
	global_load_dword v88, v74, s[100:101] nt
	global_load_dword v89, v74, s[100:101] offset:64 nt
	global_load_dword v90, v74, s[100:101] offset:512 nt
	global_load_dword v91, v74, s[100:101] offset:576 nt
	s_add_u32 s100, s100, 0x2000
	s_addc_u32 s101, s101, 0
	global_load_dword v92, v74, s[100:101] nt
	global_load_dword v93, v74, s[100:101] offset:64 nt
	global_load_dword v94, v74, s[100:101] offset:512 nt
	global_load_dword v95, v74, s[100:101] offset:576 nt
	s_add_u32 s100, s100, 0x2000
	s_addc_u32 s101, s101, 0
	global_load_dword v96, v74, s[100:101] nt
	global_load_dword v97, v74, s[100:101] offset:64 nt
	global_load_dword v152, v74, s[100:101] offset:512 nt
	global_load_dword v153, v74, s[100:101] offset:576 nt
	s_add_u32 s100, s100, 0x2000
	s_addc_u32 s101, s101, 0
	global_load_dword v154, v74, s[100:101] nt
	global_load_dword v155, v74, s[100:101] offset:64 nt
	global_load_dword v162, v74, s[100:101] offset:512 nt
	global_load_dword v163, v74, s[100:101] offset:576 nt
	s_add_u32 s100, s100, 0x1a000
	s_addc_u32 s101, s101, 0
	s_waitcnt vmcnt(32)
; #define PG8_BAR __builtin_amdgcn_s_barrier()
; template <class Epi, class Sched, bool ALIGN_EPI = false, bool SP2 = false>
; __device__ __forceinline__ void gemm_phase(PG8_LAS unsigned char* lds, const Gemm g, const Sched& S, const Epi& E, int wave_s) {
;     ...
;         if constexpr (ALIGN_EPI) { if (wr == 0) PG8_BAR; }
;         E(acc, cur, wr, wc, fr, fq); S.done(cur);
;         if (!has_next) break;
; #pragma unroll
;         for (int a = 0; a < 2; ++a)
; #pragma unroll
;             for (int b = 0; b < 2; ++b)
; #pragma unroll
;                 for (int m = 0; m < 4; ++m)
; #pragma unroll
;                     for (int n = 0; n < 2; ++n) acc[a][b][m][n] = (f32x4){0.f, 0.f, 0.f, 0.f};
;         cur = nxt; cA = nA; cB = nB; ++ui;
;         if constexpr (ALIGN_EPI) { if (wr == 1) PG8_BAR; }
;     __device__ __forceinline__ void operator()(const pg8::f32x4 (&acc)[2][2][4][2], const pg8::Unit& u, int wr, int wc, int fr, int fq) const {
;     ...
;             for (int m = 0; m < 4; ++m) { const size_t off = (size_t)(row0 + ai * 128 + m * 16) * D + col0;
; #pragma unroll
;                 for (int bj = 0; bj < 2; ++bj)
; #pragma unroll
;                     for (int n = 0; n < 2; ++n) { const pg8::f32x4 xv = *(const pg8::f32x4*)(xin + off + bj * 128 + n * 16);
;                         *(pg8::f32x4*)(xout + off + bj * 128 + n * 16) = xv + gv[bj][n] * acc[ai][bj][m][n]; }
;                 if (m & 1) asm volatile("" ::: "memory"); }
;     }
	v_fma_f32 v46, v46, v76, v164
	v_fma_f32 v42, v42, v77, v165
	v_fma_f32 v38, v38, v86, v166
	v_fma_f32 v34, v34, v87, v167
	v_fma_f32 v47, v47, v76, v168
	v_fma_f32 v43, v43, v77, v169
	v_fma_f32 v39, v39, v86, v176
	v_fma_f32 v35, v35, v87, v177
	v_fma_f32 v48, v48, v76, v178
	v_fma_f32 v44, v44, v77, v179
	v_fma_f32 v40, v40, v86, v180
	v_fma_f32 v36, v36, v87, v181
	v_fma_f32 v49, v49, v76, v182
	v_fma_f32 v45, v45, v77, v183
	v_fma_f32 v41, v41, v86, v184
	v_fma_f32 v37, v37, v87, v185
	global_store_dword v74, v46, s[18:19] nt
	global_store_dword v74, v42, s[18:19] offset:64 nt
	global_store_dword v74, v38, s[18:19] offset:512 nt
	global_store_dword v74, v34, s[18:19] offset:576 nt
	s_add_u32 s18, s18, 0x2000
	s_addc_u32 s19, s19, 0
	global_store_dword v74, v47, s[18:19] nt
	global_store_dword v74, v43, s[18:19] offset:64 nt
	global_store_dword v74, v39, s[18:19] offset:512 nt
	global_store_dword v74, v35, s[18:19] offset:576 nt
	s_add_u32 s18, s18, 0x2000
	s_addc_u32 s19, s19, 0
	global_store_dword v74, v48, s[18:19] nt
	global_store_dword v74, v44, s[18:19] offset:64 nt
	global_store_dword v74, v40, s[18:19] offset:512 nt
	global_store_dword v74, v36, s[18:19] offset:576 nt
	s_add_u32 s18, s18, 0x2000
	s_addc_u32 s19, s19, 0
	global_store_dword v74, v49, s[18:19] nt
	global_store_dword v74, v45, s[18:19] offset:64 nt
	global_store_dword v74, v41, s[18:19] offset:512 nt
	global_store_dword v74, v37, s[18:19] offset:576 nt
	s_add_u32 s18, s18, 0x1a000
	s_addc_u32 s19, s19, 0
	global_load_dword v164, v74, s[100:101] nt
	global_load_dword v165, v74, s[100:101] offset:64 nt
	global_load_dword v166, v74, s[100:101] offset:512 nt
	global_load_dword v167, v74, s[100:101] offset:576 nt
	s_add_u32 s100, s100, 0x2000
	s_addc_u32 s101, s101, 0
	global_load_dword v168, v74, s[100:101] nt
	global_load_dword v169, v74, s[100:101] offset:64 nt
	global_load_dword v176, v74, s[100:101] offset:512 nt
	global_load_dword v177, v74, s[100:101] offset:576 nt
	s_add_u32 s100, s100, 0x2000
	s_addc_u32 s101, s101, 0
	global_load_dword v178, v74, s[100:101] nt
	global_load_dword v179, v74, s[100:101] offset:64 nt
	global_load_dword v180, v74, s[100:101] offset:512 nt
	global_load_dword v181, v74, s[100:101] offset:576 nt
	s_add_u32 s100, s100, 0x2000
	s_addc_u32 s101, s101, 0
	global_load_dword v182, v74, s[100:101] nt
	global_load_dword v183, v74, s[100:101] offset:64 nt
	global_load_dword v184, v74, s[100:101] offset:512 nt
	global_load_dword v185, v74, s[100:101] offset:576 nt
	s_waitcnt vmcnt(32)
	v_fma_f32 v30, v30, v76, v88
	v_fma_f32 v26, v26, v77, v89
	v_fma_f32 v22, v22, v86, v90
	v_fma_f32 v18, v18, v87, v91
	v_fma_f32 v31, v31, v76, v92
	v_fma_f32 v27, v27, v77, v93
	v_fma_f32 v23, v23, v86, v94
	v_fma_f32 v19, v19, v87, v95
	v_fma_f32 v32, v32, v76, v96
	v_fma_f32 v28, v28, v77, v97
	v_fma_f32 v24, v24, v86, v152
	v_fma_f32 v20, v20, v87, v153
	v_fma_f32 v33, v33, v76, v154
	v_fma_f32 v29, v29, v77, v155
	v_fma_f32 v25, v25, v86, v162
	v_fma_f32 v21, v21, v87, v163
	global_store_dword v74, v30, s[18:19] nt
	global_store_dword v74, v26, s[18:19] offset:64 nt
	global_store_dword v74, v22, s[18:19] offset:512 nt
	global_store_dword v74, v18, s[18:19] offset:576 nt
	s_add_u32 s18, s18, 0x2000
	s_addc_u32 s19, s19, 0
	global_store_dword v74, v31, s[18:19] nt
	global_store_dword v74, v27, s[18:19] offset:64 nt
	global_store_dword v74, v23, s[18:19] offset:512 nt
	global_store_dword v74, v19, s[18:19] offset:576 nt
	s_add_u32 s18, s18, 0x2000
	s_addc_u32 s19, s19, 0
	global_store_dword v74, v32, s[18:19] nt
	global_store_dword v74, v28, s[18:19] offset:64 nt
	global_store_dword v74, v24, s[18:19] offset:512 nt
	global_store_dword v74, v20, s[18:19] offset:576 nt
	s_add_u32 s18, s18, 0x2000
	s_addc_u32 s19, s19, 0
	global_store_dword v74, v33, s[18:19] nt
	global_store_dword v74, v29, s[18:19] offset:64 nt
	global_store_dword v74, v25, s[18:19] offset:512 nt
	global_store_dword v74, v21, s[18:19] offset:576 nt
	s_add_u32 s18, s18, 0x1a000
	s_addc_u32 s19, s19, 0
	s_waitcnt vmcnt(16)
	v_fma_f32 v14, v14, v76, v164
	v_fma_f32 v10, v10, v77, v165
	v_fma_f32 v6, v6, v86, v166
	v_fma_f32 v2, v2, v87, v167
	v_fma_f32 v15, v15, v76, v168
	v_fma_f32 v11, v11, v77, v169
	v_fma_f32 v7, v7, v86, v176
	v_fma_f32 v3, v3, v87, v177
	v_fma_f32 v16, v16, v76, v178
	v_fma_f32 v12, v12, v77, v179
	v_fma_f32 v8, v8, v86, v180
	v_fma_f32 v4, v4, v87, v181
	v_fma_f32 v17, v17, v76, v182
	v_fma_f32 v13, v13, v77, v183
	v_fma_f32 v9, v9, v86, v184
	v_fma_f32 v5, v5, v87, v185
	global_store_dword v74, v14, s[18:19] nt
	global_store_dword v74, v10, s[18:19] offset:64 nt
	global_store_dword v74, v6, s[18:19] offset:512 nt
	global_store_dword v74, v2, s[18:19] offset:576 nt
	s_add_u32 s18, s18, 0x2000
	s_addc_u32 s19, s19, 0
	global_store_dword v74, v15, s[18:19] nt
	global_store_dword v74, v11, s[18:19] offset:64 nt
	global_store_dword v74, v7, s[18:19] offset:512 nt
	global_store_dword v74, v3, s[18:19] offset:576 nt
	s_add_u32 s18, s18, 0x2000
	s_addc_u32 s19, s19, 0
	global_store_dword v74, v16, s[18:19] nt
	global_store_dword v74, v12, s[18:19] offset:64 nt
	global_store_dword v74, v8, s[18:19] offset:512 nt
	global_store_dword v74, v4, s[18:19] offset:576 nt
	s_add_u32 s18, s18, 0x2000
	s_addc_u32 s19, s19, 0
	global_store_dword v74, v17, s[18:19] nt
	global_store_dword v74, v13, s[18:19] offset:64 nt
	global_store_dword v74, v9, s[18:19] offset:512 nt
	global_store_dword v74, v5, s[18:19] offset:576 nt
	s_mov_b64 s[18:19], -1
	s_andn2_b64 vcc, exec, s[40:41]
	s_cbranch_vccnz .LBB0_1666
	s_andn2_b64 vcc, exec, s[0:1]
	s_cbranch_vccnz .LBB0_1665
	s_barrier
	s_branch .LBB0_1665

;     __device__ __forceinline__ void operator()(const pg8::f32x4 (&acc)[2][2][4][2], const pg8::Unit& u, int wr, int wc, int fr, int fq) const {
;         const int b = u.pm >> 4;
;         const int row0 = u.pm * 256 + wr * 64 + fr, col0 = u.pn * 256 + wc * 32 + 4 * fq;
;         pg8::f32x4 gv[2][2];
; #pragma unroll
;         for (int bj = 0; bj < 2; ++bj)
; #pragma unroll
;             for (int n = 0; n < 2; ++n) gv[bj][n] = *(const pg8::f32x4*)(gate + (size_t)b * NMOD + col0 + bj * 128 + n * 16) * coef;
; #pragma unroll
;         for (int ai = 0; ai < 2; ++ai)
; #pragma unroll
;             for (int m = 0; m < 4; ++m) { const size_t off = (size_t)(row0 + ai * 128 + m * 16) * D + col0;
; #pragma unroll
;                 for (int bj = 0; bj < 2; ++bj)
; #pragma unroll
;                     for (int n = 0; n < 2; ++n) { const pg8::f32x4 xv = *(const pg8::f32x4*)(xin + off + bj * 128 + n * 16);
;                         *(pg8::f32x4*)(xout + off + bj * 128 + n * 16) = xv + gv[bj][n] * acc[ai][bj][m][n]; }
;                 if (m & 1) asm volatile("" ::: "memory"); }
;     }
.LBB0_1873:
	v_and_b32_e32 v136, 0x40, v158
	v_and_b32_e32 v137, 12, v160
	v_or_b32_e32 v136, v136, v137
	v_and_b32_e32 v137, 0x60, v160
	v_and_or_b32 v137, v158, 15, v137
	v_lshlrev_b32_e32 v137, 2, v137
	v_lshl_add_u32 v136, v136, 13, v137
	s_ashr_i32 vcc_hi, s51, 4
	s_mul_i32 vcc_hi, vcc_hi, 0x12000
	s_lshl_b32 vcc_lo, s26, 10
	s_add_u32 vcc_hi, vcc_hi, vcc_lo
	s_add_u32 s14, s44, vcc_hi
	s_addc_u32 s15, s45, 0
	global_load_dword v138, v137, s[14:15]
	global_load_dword v139, v137, s[14:15] offset:64
	global_load_dword v140, v137, s[14:15] offset:512
	global_load_dword v141, v137, s[14:15] offset:576
	s_lshl_b32 vcc_hi, s51, 21
	s_add_u32 vcc_lo, vcc_lo, vcc_hi
	s_add_u32 s100, s6, vcc_lo
	s_addc_u32 s101, s7, 0
	s_add_u32 s14, s6, vcc_lo
	s_addc_u32 s15, s7, 0
	global_load_dword v142, v136, s[100:101] nt
	global_load_dword v143, v136, s[100:101] offset:64 nt
	global_load_dword v144, v136, s[100:101] offset:512 nt
	global_load_dword v145, v136, s[100:101] offset:576 nt
	s_add_u32 s100, s100, 0x2000
	s_addc_u32 s101, s101, 0
	global_load_dword v146, v136, s[100:101] nt
	global_load_dword v147, v136, s[100:101] offset:64 nt
	global_load_dword v148, v136, s[100:101] offset:512 nt
	global_load_dword v149, v136, s[100:101] offset:576 nt
	s_add_u32 s100, s100, 0x2000
	s_addc_u32 s101, s101, 0
	global_load_dword v150, v136, s[100:101] nt
	global_load_dword v151, v136, s[100:101] offset:64 nt
	global_load_dword v152, v136, s[100:101] offset:512 nt
	global_load_dword v153, v136, s[100:101] offset:576 nt
	s_add_u32 s100, s100, 0x2000
	s_addc_u32 s101, s101, 0
	global_load_dword v154, v136, s[100:101] nt
	global_load_dword v155, v136, s[100:101] offset:64 nt
	global_load_dword v162, v136, s[100:101] offset:512 nt
	global_load_dword v163, v136, s[100:101] offset:576 nt
	s_add_u32 s100, s100, 0x1a000
	s_addc_u32 s101, s101, 0
	global_load_dword v164, v136, s[100:101] nt
	global_load_dword v165, v136, s[100:101] offset:64 nt
	global_load_dword v166, v136, s[100:101] offset:512 nt
	global_load_dword v167, v136, s[100:101] offset:576 nt
	s_add_u32 s100, s100, 0x2000
	s_addc_u32 s101, s101, 0
	global_load_dword v168, v136, s[100:101] nt
	global_load_dword v169, v136, s[100:101] offset:64 nt
	global_load_dword v176, v136, s[100:101] offset:512 nt
	global_load_dword v177, v136, s[100:101] offset:576 nt
	s_add_u32 s100, s100, 0x2000
	s_addc_u32 s101, s101, 0
	global_load_dword v178, v136, s[100:101] nt
	global_load_dword v179, v136, s[100:101] offset:64 nt
	global_load_dword v180, v136, s[100:101] offset:512 nt
	global_load_dword v181, v136, s[100:101] offset:576 nt
	s_add_u32 s100, s100, 0x2000
	s_addc_u32 s101, s101, 0
	global_load_dword v182, v136, s[100:101] nt
	global_load_dword v183, v136, s[100:101] offset:64 nt
	global_load_dword v184, v136, s[100:101] offset:512 nt
	global_load_dword v185, v136, s[100:101] offset:576 nt
	s_add_u32 s100, s100, 0x1a000
	s_addc_u32 s101, s101, 0
	s_waitcnt vmcnt(16)
	v_mul_f32_e32 v138, 0.5, v138
	v_mul_f32_e32 v139, 0.5, v139
	v_mul_f32_e32 v140, 0.5, v140
	v_mul_f32_e32 v141, 0.5, v141
	v_fma_f32 v126, v126, v138, v142
	v_fma_f32 v122, v122, v139, v143
	v_fma_f32 v118, v118, v140, v144
	v_fma_f32 v114, v114, v141, v145
	v_fma_f32 v127, v127, v138, v146
	v_fma_f32 v123, v123, v139, v147
	v_fma_f32 v119, v119, v140, v148
	v_fma_f32 v115, v115, v141, v149
	v_fma_f32 v128, v128, v138, v150
	v_fma_f32 v124, v124, v139, v151
	v_fma_f32 v120, v120, v140, v152
	v_fma_f32 v116, v116, v141, v153
	v_fma_f32 v129, v129, v138, v154
	v_fma_f32 v125, v125, v139, v155
	v_fma_f32 v121, v121, v140, v162
	v_fma_f32 v117, v117, v141, v163
	global_store_dword v136, v126, s[14:15] nt
	global_store_dword v136, v122, s[14:15] offset:64 nt
	global_store_dword v136, v118, s[14:15] offset:512 nt
	global_store_dword v136, v114, s[14:15] offset:576 nt
	s_add_u32 s14, s14, 0x2000
	s_addc_u32 s15, s15, 0
	global_store_dword v136, v127, s[14:15] nt
	global_store_dword v136, v123, s[14:15] offset:64 nt
	global_store_dword v136, v119, s[14:15] offset:512 nt
	global_store_dword v136, v115, s[14:15] offset:576 nt
	s_add_u32 s14, s14, 0x2000
	s_addc_u32 s15, s15, 0
	global_store_dword v136, v128, s[14:15] nt
	global_store_dword v136, v124, s[14:15] offset:64 nt
	global_store_dword v136, v120, s[14:15] offset:512 nt
	global_store_dword v136, v116, s[14:15] offset:576 nt
	s_add_u32 s14, s14, 0x2000
	s_addc_u32 s15, s15, 0
	global_store_dword v136, v129, s[14:15] nt
	global_store_dword v136, v125, s[14:15] offset:64 nt
	global_store_dword v136, v121, s[14:15] offset:512 nt
	global_store_dword v136, v117, s[14:15] offset:576 nt
	s_add_u32 s14, s14, 0x1a000
	s_addc_u32 s15, s15, 0
	global_load_dword v142, v136, s[100:101] nt
	global_load_dword v143, v136, s[100:101] offset:64 nt
	global_load_dword v144, v136, s[100:101] offset:512 nt
	global_load_dword v145, v136, s[100:101] offset:576 nt
	s_add_u32 s100, s100, 0x2000
	s_addc_u32 s101, s101, 0
	global_load_dword v146, v136, s[100:101] nt
	global_load_dword v147, v136, s[100:101] offset:64 nt
	global_load_dword v148, v136, s[100:101] offset:512 nt
	global_load_dword v149, v136, s[100:101] offset:576 nt
	s_add_u32 s100, s100, 0x2000
	s_addc_u32 s101, s101, 0
	global_load_dword v150, v136, s[100:101] nt
	global_load_dword v151, v136, s[100:101] offset:64 nt
	global_load_dword v152, v136, s[100:101] offset:512 nt
	global_load_dword v153, v136, s[100:101] offset:576 nt
	s_add_u32 s100, s100, 0x2000
	s_addc_u32 s101, s101, 0
	global_load_dword v154, v136, s[100:101] nt
	global_load_dword v155, v136, s[100:101] offset:64 nt
	global_load_dword v162, v136, s[100:101] offset:512 nt
	global_load_dword v163, v136, s[100:101] offset:576 nt
	s_add_u32 s100, s100, 0x1a000
	s_addc_u32 s101, s101, 0
	s_waitcnt vmcnt(32)
;     __device__ __forceinline__ void operator()(const pg8::f32x4 (&acc)[2][2][4][2], const pg8::Unit& u, int wr, int wc, int fr, int fq) const {
;     ...
;             for (int m = 0; m < 4; ++m) { const size_t off = (size_t)(row0 + ai * 128 + m * 16) * D + col0;
; #pragma unroll
;                 for (int bj = 0; bj < 2; ++bj)
; #pragma unroll
;                     for (int n = 0; n < 2; ++n) { const pg8::f32x4 xv = *(const pg8::f32x4*)(xin + off + bj * 128 + n * 16);
;                         *(pg8::f32x4*)(xout + off + bj * 128 + n * 16) = xv + gv[bj][n] * acc[ai][bj][m][n]; }
;                 if (m & 1) asm volatile("" ::: "memory"); }
;     }
	v_fma_f32 v110, v110, v138, v164
	v_fma_f32 v106, v106, v139, v165
	v_fma_f32 v102, v102, v140, v166
	v_fma_f32 v98, v98, v141, v167
	v_fma_f32 v111, v111, v138, v168
	v_fma_f32 v107, v107, v139, v169
	v_fma_f32 v103, v103, v140, v176
	v_fma_f32 v99, v99, v141, v177
	v_fma_f32 v112, v112, v138, v178
	v_fma_f32 v108, v108, v139, v179
	v_fma_f32 v104, v104, v140, v180
	v_fma_f32 v100, v100, v141, v181
	v_fma_f32 v113, v113, v138, v182
	v_fma_f32 v109, v109, v139, v183
	v_fma_f32 v105, v105, v140, v184
	v_fma_f32 v101, v101, v141, v185
	global_store_dword v136, v110, s[14:15] nt
	global_store_dword v136, v106, s[14:15] offset:64 nt
	global_store_dword v136, v102, s[14:15] offset:512 nt
	global_store_dword v136, v98, s[14:15] offset:576 nt
	s_add_u32 s14, s14, 0x2000
	s_addc_u32 s15, s15, 0
	global_store_dword v136, v111, s[14:15] nt
	global_store_dword v136, v107, s[14:15] offset:64 nt
	global_store_dword v136, v103, s[14:15] offset:512 nt
	global_store_dword v136, v99, s[14:15] offset:576 nt
	s_add_u32 s14, s14, 0x2000
	s_addc_u32 s15, s15, 0
	global_store_dword v136, v112, s[14:15] nt
	global_store_dword v136, v108, s[14:15] offset:64 nt
	global_store_dword v136, v104, s[14:15] offset:512 nt
	global_store_dword v136, v100, s[14:15] offset:576 nt
	s_add_u32 s14, s14, 0x2000
	s_addc_u32 s15, s15, 0
	global_store_dword v136, v113, s[14:15] nt
	global_store_dword v136, v109, s[14:15] offset:64 nt
	global_store_dword v136, v105, s[14:15] offset:512 nt
	global_store_dword v136, v101, s[14:15] offset:576 nt
	s_add_u32 s14, s14, 0x1a000
	s_addc_u32 s15, s15, 0
	global_load_dword v164, v136, s[100:101] nt
	global_load_dword v165, v136, s[100:101] offset:64 nt
	global_load_dword v166, v136, s[100:101] offset:512 nt
	global_load_dword v167, v136, s[100:101] offset:576 nt
	s_add_u32 s100, s100, 0x2000
	s_addc_u32 s101, s101, 0
	global_load_dword v168, v136, s[100:101] nt
	global_load_dword v169, v136, s[100:101] offset:64 nt
	global_load_dword v176, v136, s[100:101] offset:512 nt
	global_load_dword v177, v136, s[100:101] offset:576 nt
	s_add_u32 s100, s100, 0x2000
	s_addc_u32 s101, s101, 0
	global_load_dword v178, v136, s[100:101] nt
	global_load_dword v179, v136, s[100:101] offset:64 nt
	global_load_dword v180, v136, s[100:101] offset:512 nt
	global_load_dword v181, v136, s[100:101] offset:576 nt
	s_add_u32 s100, s100, 0x2000
	s_addc_u32 s101, s101, 0
	global_load_dword v182, v136, s[100:101] nt
	global_load_dword v183, v136, s[100:101] offset:64 nt
	global_load_dword v184, v136, s[100:101] offset:512 nt
	global_load_dword v185, v136, s[100:101] offset:576 nt
	s_add_u32 s100, s100, 0x9a000
	s_addc_u32 s101, s101, 0
	s_waitcnt vmcnt(32)
	v_fma_f32 v94, v94, v138, v142
	v_fma_f32 v90, v90, v139, v143
	v_fma_f32 v86, v86, v140, v144
	v_fma_f32 v82, v82, v141, v145
	v_fma_f32 v95, v95, v138, v146
	v_fma_f32 v91, v91, v139, v147
	v_fma_f32 v87, v87, v140, v148
	v_fma_f32 v83, v83, v141, v149
	v_fma_f32 v96, v96, v138, v150
	v_fma_f32 v92, v92, v139, v151
	v_fma_f32 v88, v88, v140, v152
	v_fma_f32 v84, v84, v141, v153
	v_fma_f32 v97, v97, v138, v154
	v_fma_f32 v93, v93, v139, v155
	v_fma_f32 v89, v89, v140, v162
	v_fma_f32 v85, v85, v141, v163
	global_store_dword v136, v94, s[14:15] nt
	global_store_dword v136, v90, s[14:15] offset:64 nt
	global_store_dword v136, v86, s[14:15] offset:512 nt
	global_store_dword v136, v82, s[14:15] offset:576 nt
	s_add_u32 s14, s14, 0x2000
	s_addc_u32 s15, s15, 0
	global_store_dword v136, v95, s[14:15] nt
	global_store_dword v136, v91, s[14:15] offset:64 nt
	global_store_dword v136, v87, s[14:15] offset:512 nt
	global_store_dword v136, v83, s[14:15] offset:576 nt
	s_add_u32 s14, s14, 0x2000
	s_addc_u32 s15, s15, 0
	global_store_dword v136, v96, s[14:15] nt
	global_store_dword v136, v92, s[14:15] offset:64 nt
	global_store_dword v136, v88, s[14:15] offset:512 nt
	global_store_dword v136, v84, s[14:15] offset:576 nt
	s_add_u32 s14, s14, 0x2000
	s_addc_u32 s15, s15, 0
	global_store_dword v136, v97, s[14:15] nt
	global_store_dword v136, v93, s[14:15] offset:64 nt
	global_store_dword v136, v89, s[14:15] offset:512 nt
	global_store_dword v136, v85, s[14:15] offset:576 nt
	s_add_u32 s14, s14, 0x1a000
	s_addc_u32 s15, s15, 0
	global_load_dword v142, v136, s[100:101] nt
	global_load_dword v143, v136, s[100:101] offset:64 nt
	global_load_dword v144, v136, s[100:101] offset:512 nt
	global_load_dword v145, v136, s[100:101] offset:576 nt
	s_add_u32 s100, s100, 0x2000
	s_addc_u32 s101, s101, 0
	global_load_dword v146, v136, s[100:101] nt
	global_load_dword v147, v136, s[100:101] offset:64 nt
	global_load_dword v148, v136, s[100:101] offset:512 nt
	global_load_dword v149, v136, s[100:101] offset:576 nt
	s_add_u32 s100, s100, 0x2000
	s_addc_u32 s101, s101, 0
	global_load_dword v150, v136, s[100:101] nt
	global_load_dword v151, v136, s[100:101] offset:64 nt
	global_load_dword v152, v136, s[100:101] offset:512 nt
	global_load_dword v153, v136, s[100:101] offset:576 nt
	s_add_u32 s100, s100, 0x2000
	s_addc_u32 s101, s101, 0
	global_load_dword v154, v136, s[100:101] nt
	global_load_dword v155, v136, s[100:101] offset:64 nt
	global_load_dword v162, v136, s[100:101] offset:512 nt
	global_load_dword v163, v136, s[100:101] offset:576 nt
	s_add_u32 s100, s100, 0x1a000
	s_addc_u32 s101, s101, 0
	s_waitcnt vmcnt(32)
;     __device__ __forceinline__ void operator()(const pg8::f32x4 (&acc)[2][2][4][2], const pg8::Unit& u, int wr, int wc, int fr, int fq) const {
;     ...
;             for (int m = 0; m < 4; ++m) { const size_t off = (size_t)(row0 + ai * 128 + m * 16) * D + col0;
; #pragma unroll
;                 for (int bj = 0; bj < 2; ++bj)
; #pragma unroll
;                     for (int n = 0; n < 2; ++n) { const pg8::f32x4 xv = *(const pg8::f32x4*)(xin + off + bj * 128 + n * 16);
;                         *(pg8::f32x4*)(xout + off + bj * 128 + n * 16) = xv + gv[bj][n] * acc[ai][bj][m][n]; }
;                 if (m & 1) asm volatile("" ::: "memory"); }
;     }
	v_fma_f32 v78, v78, v138, v164
	v_fma_f32 v74, v74, v139, v165
	v_fma_f32 v70, v70, v140, v166
	v_fma_f32 v66, v66, v141, v167
	v_fma_f32 v79, v79, v138, v168
	v_fma_f32 v75, v75, v139, v169
	v_fma_f32 v71, v71, v140, v176
	v_fma_f32 v67, v67, v141, v177
	v_fma_f32 v80, v80, v138, v178
	v_fma_f32 v76, v76, v139, v179
	v_fma_f32 v72, v72, v140, v180
	v_fma_f32 v68, v68, v141, v181
	v_fma_f32 v81, v81, v138, v182
	v_fma_f32 v77, v77, v139, v183
	v_fma_f32 v73, v73, v140, v184
	v_fma_f32 v69, v69, v141, v185
	global_store_dword v136, v78, s[14:15] nt
	global_store_dword v136, v74, s[14:15] offset:64 nt
	global_store_dword v136, v70, s[14:15] offset:512 nt
	global_store_dword v136, v66, s[14:15] offset:576 nt
	s_add_u32 s14, s14, 0x2000
	s_addc_u32 s15, s15, 0
	global_store_dword v136, v79, s[14:15] nt
	global_store_dword v136, v75, s[14:15] offset:64 nt
	global_store_dword v136, v71, s[14:15] offset:512 nt
	global_store_dword v136, v67, s[14:15] offset:576 nt
	s_add_u32 s14, s14, 0x2000
	s_addc_u32 s15, s15, 0
	global_store_dword v136, v80, s[14:15] nt
	global_store_dword v136, v76, s[14:15] offset:64 nt
	global_store_dword v136, v72, s[14:15] offset:512 nt
	global_store_dword v136, v68, s[14:15] offset:576 nt
	s_add_u32 s14, s14, 0x2000
	s_addc_u32 s15, s15, 0
	global_store_dword v136, v81, s[14:15] nt
	global_store_dword v136, v77, s[14:15] offset:64 nt
	global_store_dword v136, v73, s[14:15] offset:512 nt
	global_store_dword v136, v69, s[14:15] offset:576 nt
	s_add_u32 s14, s14, 0x9a000
	s_addc_u32 s15, s15, 0
	global_load_dword v164, v136, s[100:101] nt
	global_load_dword v165, v136, s[100:101] offset:64 nt
	global_load_dword v166, v136, s[100:101] offset:512 nt
	global_load_dword v167, v136, s[100:101] offset:576 nt
	s_add_u32 s100, s100, 0x2000
	s_addc_u32 s101, s101, 0
	global_load_dword v168, v136, s[100:101] nt
	global_load_dword v169, v136, s[100:101] offset:64 nt
	global_load_dword v176, v136, s[100:101] offset:512 nt
	global_load_dword v177, v136, s[100:101] offset:576 nt
	s_add_u32 s100, s100, 0x2000
	s_addc_u32 s101, s101, 0
	global_load_dword v178, v136, s[100:101] nt
	global_load_dword v179, v136, s[100:101] offset:64 nt
	global_load_dword v180, v136, s[100:101] offset:512 nt
	global_load_dword v181, v136, s[100:101] offset:576 nt
	s_add_u32 s100, s100, 0x2000
	s_addc_u32 s101, s101, 0
	global_load_dword v182, v136, s[100:101] nt
	global_load_dword v183, v136, s[100:101] offset:64 nt
	global_load_dword v184, v136, s[100:101] offset:512 nt
	global_load_dword v185, v136, s[100:101] offset:576 nt
	s_add_u32 s100, s100, 0x1a000
	s_addc_u32 s101, s101, 0
	s_waitcnt vmcnt(32)
	v_fma_f32 v62, v62, v138, v142
	v_fma_f32 v58, v58, v139, v143
	v_fma_f32 v54, v54, v140, v144
	v_fma_f32 v50, v50, v141, v145
	v_fma_f32 v63, v63, v138, v146
	v_fma_f32 v59, v59, v139, v147
	v_fma_f32 v55, v55, v140, v148
	v_fma_f32 v51, v51, v141, v149
	v_fma_f32 v64, v64, v138, v150
	v_fma_f32 v60, v60, v139, v151
	v_fma_f32 v56, v56, v140, v152
	v_fma_f32 v52, v52, v141, v153
	v_fma_f32 v65, v65, v138, v154
	v_fma_f32 v61, v61, v139, v155
	v_fma_f32 v57, v57, v140, v162
	v_fma_f32 v53, v53, v141, v163
	global_store_dword v136, v62, s[14:15] nt
	global_store_dword v136, v58, s[14:15] offset:64 nt
	global_store_dword v136, v54, s[14:15] offset:512 nt
	global_store_dword v136, v50, s[14:15] offset:576 nt
	s_add_u32 s14, s14, 0x2000
	s_addc_u32 s15, s15, 0
	global_store_dword v136, v63, s[14:15] nt
	global_store_dword v136, v59, s[14:15] offset:64 nt
	global_store_dword v136, v55, s[14:15] offset:512 nt
	global_store_dword v136, v51, s[14:15] offset:576 nt
	s_add_u32 s14, s14, 0x2000
	s_addc_u32 s15, s15, 0
	global_store_dword v136, v64, s[14:15] nt
	global_store_dword v136, v60, s[14:15] offset:64 nt
	global_store_dword v136, v56, s[14:15] offset:512 nt
	global_store_dword v136, v52, s[14:15] offset:576 nt
	s_add_u32 s14, s14, 0x2000
	s_addc_u32 s15, s15, 0
	global_store_dword v136, v65, s[14:15] nt
	global_store_dword v136, v61, s[14:15] offset:64 nt
	global_store_dword v136, v57, s[14:15] offset:512 nt
	global_store_dword v136, v53, s[14:15] offset:576 nt
	s_add_u32 s14, s14, 0x1a000
	s_addc_u32 s15, s15, 0
	global_load_dword v142, v136, s[100:101] nt
	global_load_dword v143, v136, s[100:101] offset:64 nt
	global_load_dword v144, v136, s[100:101] offset:512 nt
	global_load_dword v145, v136, s[100:101] offset:576 nt
	s_add_u32 s100, s100, 0x2000
	s_addc_u32 s101, s101, 0
	global_load_dword v146, v136, s[100:101] nt
	global_load_dword v147, v136, s[100:101] offset:64 nt
	global_load_dword v148, v136, s[100:101] offset:512 nt
	global_load_dword v149, v136, s[100:101] offset:576 nt
	s_add_u32 s100, s100, 0x2000
	s_addc_u32 s101, s101, 0
	global_load_dword v150, v136, s[100:101] nt
	global_load_dword v151, v136, s[100:101] offset:64 nt
	global_load_dword v152, v136, s[100:101] offset:512 nt
	global_load_dword v153, v136, s[100:101] offset:576 nt
	s_add_u32 s100, s100, 0x2000
	s_addc_u32 s101, s101, 0
	global_load_dword v154, v136, s[100:101] nt
	global_load_dword v155, v136, s[100:101] offset:64 nt
	global_load_dword v162, v136, s[100:101] offset:512 nt
	global_load_dword v163, v136, s[100:101] offset:576 nt
	s_add_u32 s100, s100, 0x1a000
	s_addc_u32 s101, s101, 0
	s_waitcnt vmcnt(32)
; #define PG8_BAR __builtin_amdgcn_s_barrier()
; template <class Epi, class Sched, bool ALIGN_EPI = false, bool SP2 = false>
; __device__ __forceinline__ void gemm_phase(PG8_LAS unsigned char* lds, const Gemm g, const Sched& S, const Epi& E, int wave_s) {
;     ...
;         if constexpr (ALIGN_EPI) { if (wr == 0) PG8_BAR; }
;         E(acc, cur, wr, wc, fr, fq); S.done(cur);
;         if (!has_next) break;
; #pragma unroll
;         for (int a = 0; a < 2; ++a)
; #pragma unroll
;             for (int b = 0; b < 2; ++b)
; #pragma unroll
;                 for (int m = 0; m < 4; ++m)
; #pragma unroll
;                     for (int n = 0; n < 2; ++n) acc[a][b][m][n] = (f32x4){0.f, 0.f, 0.f, 0.f};
;         cur = nxt; cA = nA; cB = nB; ++ui;
;         if constexpr (ALIGN_EPI) { if (wr == 1) PG8_BAR; }
;     __device__ __forceinline__ void operator()(const pg8::f32x4 (&acc)[2][2][4][2], const pg8::Unit& u, int wr, int wc, int fr, int fq) const {
;     ...
;             for (int m = 0; m < 4; ++m) { const size_t off = (size_t)(row0 + ai * 128 + m * 16) * D + col0;
; #pragma unroll
;                 for (int bj = 0; bj < 2; ++bj)
; #pragma unroll
;                     for (int n = 0; n < 2; ++n) { const pg8::f32x4 xv = *(const pg8::f32x4*)(xin + off + bj * 128 + n * 16);
;                         *(pg8::f32x4*)(xout + off + bj * 128 + n * 16) = xv + gv[bj][n] * acc[ai][bj][m][n]; }
;                 if (m & 1) asm volatile("" ::: "memory"); }
;     }
	v_fma_f32 v46, v46, v138, v164
	v_fma_f32 v42, v42, v139, v165
	v_fma_f32 v38, v38, v140, v166
	v_fma_f32 v34, v34, v141, v167
	v_fma_f32 v47, v47, v138, v168
	v_fma_f32 v43, v43, v139, v169
	v_fma_f32 v39, v39, v140, v176
	v_fma_f32 v35, v35, v141, v177
	v_fma_f32 v48, v48, v138, v178
	v_fma_f32 v44, v44, v139, v179
	v_fma_f32 v40, v40, v140, v180
	v_fma_f32 v36, v36, v141, v181
	v_fma_f32 v49, v49, v138, v182
	v_fma_f32 v45, v45, v139, v183
	v_fma_f32 v41, v41, v140, v184
	v_fma_f32 v37, v37, v141, v185
	global_store_dword v136, v46, s[14:15] nt
	global_store_dword v136, v42, s[14:15] offset:64 nt
	global_store_dword v136, v38, s[14:15] offset:512 nt
	global_store_dword v136, v34, s[14:15] offset:576 nt
	s_add_u32 s14, s14, 0x2000
	s_addc_u32 s15, s15, 0
	global_store_dword v136, v47, s[14:15] nt
	global_store_dword v136, v43, s[14:15] offset:64 nt
	global_store_dword v136, v39, s[14:15] offset:512 nt
	global_store_dword v136, v35, s[14:15] offset:576 nt
	s_add_u32 s14, s14, 0x2000
	s_addc_u32 s15, s15, 0
	global_store_dword v136, v48, s[14:15] nt
	global_store_dword v136, v44, s[14:15] offset:64 nt
	global_store_dword v136, v40, s[14:15] offset:512 nt
	global_store_dword v136, v36, s[14:15] offset:576 nt
	s_add_u32 s14, s14, 0x2000
	s_addc_u32 s15, s15, 0
	global_store_dword v136, v49, s[14:15] nt
	global_store_dword v136, v45, s[14:15] offset:64 nt
	global_store_dword v136, v41, s[14:15] offset:512 nt
	global_store_dword v136, v37, s[14:15] offset:576 nt
	s_add_u32 s14, s14, 0x1a000
	s_addc_u32 s15, s15, 0
	global_load_dword v164, v136, s[100:101] nt
	global_load_dword v165, v136, s[100:101] offset:64 nt
	global_load_dword v166, v136, s[100:101] offset:512 nt
	global_load_dword v167, v136, s[100:101] offset:576 nt
	s_add_u32 s100, s100, 0x2000
	s_addc_u32 s101, s101, 0
	global_load_dword v168, v136, s[100:101] nt
	global_load_dword v169, v136, s[100:101] offset:64 nt
	global_load_dword v176, v136, s[100:101] offset:512 nt
	global_load_dword v177, v136, s[100:101] offset:576 nt
	s_add_u32 s100, s100, 0x2000
	s_addc_u32 s101, s101, 0
	global_load_dword v178, v136, s[100:101] nt
	global_load_dword v179, v136, s[100:101] offset:64 nt
	global_load_dword v180, v136, s[100:101] offset:512 nt
	global_load_dword v181, v136, s[100:101] offset:576 nt
	s_add_u32 s100, s100, 0x2000
	s_addc_u32 s101, s101, 0
	global_load_dword v182, v136, s[100:101] nt
	global_load_dword v183, v136, s[100:101] offset:64 nt
	global_load_dword v184, v136, s[100:101] offset:512 nt
	global_load_dword v185, v136, s[100:101] offset:576 nt
	s_waitcnt vmcnt(32)
	v_fma_f32 v30, v30, v138, v142
	v_fma_f32 v26, v26, v139, v143
	v_fma_f32 v22, v22, v140, v144
	v_fma_f32 v18, v18, v141, v145
	v_fma_f32 v31, v31, v138, v146
	v_fma_f32 v27, v27, v139, v147
	v_fma_f32 v23, v23, v140, v148
	v_fma_f32 v19, v19, v141, v149
	v_fma_f32 v32, v32, v138, v150
	v_fma_f32 v28, v28, v139, v151
	v_fma_f32 v24, v24, v140, v152
	v_fma_f32 v20, v20, v141, v153
	v_fma_f32 v33, v33, v138, v154
	v_fma_f32 v29, v29, v139, v155
	v_fma_f32 v25, v25, v140, v162
	v_fma_f32 v21, v21, v141, v163
	global_store_dword v136, v30, s[14:15] nt
	global_store_dword v136, v26, s[14:15] offset:64 nt
	global_store_dword v136, v22, s[14:15] offset:512 nt
	global_store_dword v136, v18, s[14:15] offset:576 nt
	s_add_u32 s14, s14, 0x2000
	s_addc_u32 s15, s15, 0
	global_store_dword v136, v31, s[14:15] nt
	global_store_dword v136, v27, s[14:15] offset:64 nt
	global_store_dword v136, v23, s[14:15] offset:512 nt
	global_store_dword v136, v19, s[14:15] offset:576 nt
	s_add_u32 s14, s14, 0x2000
	s_addc_u32 s15, s15, 0
	global_store_dword v136, v32, s[14:15] nt
	global_store_dword v136, v28, s[14:15] offset:64 nt
	global_store_dword v136, v24, s[14:15] offset:512 nt
	global_store_dword v136, v20, s[14:15] offset:576 nt
	s_add_u32 s14, s14, 0x2000
	s_addc_u32 s15, s15, 0
	global_store_dword v136, v33, s[14:15] nt
	global_store_dword v136, v29, s[14:15] offset:64 nt
	global_store_dword v136, v25, s[14:15] offset:512 nt
	global_store_dword v136, v21, s[14:15] offset:576 nt
	s_add_u32 s14, s14, 0x1a000
	s_addc_u32 s15, s15, 0
	s_waitcnt vmcnt(16)
	v_fma_f32 v14, v14, v138, v164
	v_fma_f32 v10, v10, v139, v165
	v_fma_f32 v6, v6, v140, v166
	v_fma_f32 v2, v2, v141, v167
	v_fma_f32 v15, v15, v138, v168
	v_fma_f32 v11, v11, v139, v169
	v_fma_f32 v7, v7, v140, v176
	v_fma_f32 v3, v3, v141, v177
	v_fma_f32 v16, v16, v138, v178
	v_fma_f32 v12, v12, v139, v179
	v_fma_f32 v8, v8, v140, v180
	v_fma_f32 v4, v4, v141, v181
	v_fma_f32 v17, v17, v138, v182
	v_fma_f32 v13, v13, v139, v183
	v_fma_f32 v9, v9, v140, v184
	v_fma_f32 v5, v5, v141, v185
	global_store_dword v136, v14, s[14:15] nt
	global_store_dword v136, v10, s[14:15] offset:64 nt
	global_store_dword v136, v6, s[14:15] offset:512 nt
	global_store_dword v136, v2, s[14:15] offset:576 nt
	s_add_u32 s14, s14, 0x2000
	s_addc_u32 s15, s15, 0
	global_store_dword v136, v15, s[14:15] nt
	global_store_dword v136, v11, s[14:15] offset:64 nt
	global_store_dword v136, v7, s[14:15] offset:512 nt
	global_store_dword v136, v3, s[14:15] offset:576 nt
	s_add_u32 s14, s14, 0x2000
	s_addc_u32 s15, s15, 0
	global_store_dword v136, v16, s[14:15] nt
	global_store_dword v136, v12, s[14:15] offset:64 nt
	global_store_dword v136, v8, s[14:15] offset:512 nt
	global_store_dword v136, v4, s[14:15] offset:576 nt
	s_add_u32 s14, s14, 0x2000
	s_addc_u32 s15, s15, 0
	global_store_dword v136, v17, s[14:15] nt
	global_store_dword v136, v13, s[14:15] offset:64 nt
	global_store_dword v136, v9, s[14:15] offset:512 nt
	global_store_dword v136, v5, s[14:15] offset:576 nt
	s_mov_b64 s[14:15], -1
	s_and_b64 vcc, exec, s[36:37]
	s_cbranch_vccnz .LBB0_1858
	s_andn2_b64 vcc, exec, s[0:1]
	s_cbranch_vccnz .LBB0_1857
	s_barrier
	s_branch .LBB0_1857
